# full-line stores in P1 epilogue: within-wave LDS transpose so each global_store_dwordx4 writes 8 full 128B lines (plain + q/k paths, bf16 and f32 outputs)
# speedup vs baseline: 1.0249x; 1.0249x over previous
;     __host__ __device__ bool next(int i, Unit& u) const { if (PROBE_DUP == 1 && nN == 32) { if (i >= 66) return false; if (i >= 33) i -= 33; } return map((long)i * G + c, u); }
;     __host__ __device__ bool next(int i, Unit& u) const { if (!b.map((long)(i >> 1) * b.G + b.c, u)) return false; u.kp = i & 1; return true; }
; template <class Epi, class Sched, bool ALIGN_EPI>
; __device__ __forceinline__ unsigned long long gemm_phase(PG8_LAS unsigned char* lds, const Gemm g, const Sched& S, const Epi& E, const int probe_id) {
;     ...
;     const int tid = threadIdx.x, wid = __builtin_amdgcn_readfirstlane(tid >> 6), lane = tid & 63, wr = wid >> 2, wc = wid & 3, fr = lane & 15, fq = lane >> 4;
;     const int K = g.K, nt = K / BK;
;     unsigned voffA[2], voffB[2];
; #pragma unroll
;     for (int i = 0; i < 2; ++i) { int R, C; stage_rc(tid * 16 + i * 8192, R, C); const int Rb = Epi::PERM ? ((R & ~31) + perm32(R & 31)) : R;
;         voffA[i] = (unsigned)(R * g.lda + C) * 2u; voffB[i] = (unsigned)(Rb * g.ldb + C) * 2u; }
;     const size_t kstep = (size_t)(BK * 2);
;     const size_t hstepA = (size_t)HALF * g.lda * 2, hstepB = (size_t)HALF * g.ldb * 2;
;     const size_t tstepA = 2 * hstepA, tstepB = 2 * hstepB;
;     const unsigned ldsw = (unsigned)wid * 1024u;
;     const int aoff = lds_byte(wr * 64 + fr, fq * 8), boff = lds_byte(wc * 32 + fr, fq * 8);
;     ...
;     Unit cur, nxt; int ui = 0;
;     if (!S.next(0, cur)) return 0;
;     f32x4 acc[2][2][4][2];
; #pragma unroll
;     for (int a = 0; a < 2; ++a)
; #pragma unroll
;         for (int b = 0; b < 2; ++b)
; #pragma unroll
;             for (int m = 0; m < 4; ++m)
; #pragma unroll
;                 for (int n = 0; n < 2; ++n) acc[a][b][m][n] = (f32x4){0.f, 0.f, 0.f, 0.f};
;     bf16x8 At[4][2], B0[2][2], B1[2][2];
;     const char* cA = (const char*)g.A + (size_t)cur.pm * tstepA + (size_t)cur.kp * K * 2; const char* cB = (const char*)g.Bt + (size_t)cur.pn * tstepB + (size_t)cur.kp * K * 2;
;     PG8_STAGE(PG8_SB(0, 0), cB, voffB); PG8_STAGE(PG8_SB(0, 1), cB + hstepB, voffB); PG8_STAGE(PG8_SA(0, 0), cA, voffA); PG8_STAGE(PG8_SA(0, 1), cA + hstepA, voffA);
;     if (wr == 1) PG8_BAR;
;     PG8_WAIT_V(2); PG8_BAR;
;     PG8_STAGE(PG8_SB(1, 0), cB + kstep, voffB); PG8_STAGE(PG8_SA(1, 0), cA + kstep, voffA); PG8_STAGE(PG8_SB(1, 1), cB + hstepB + kstep, voffB);
;     PG8_WAIT_V(6); PG8_BAR;
.LBB0_114:
	s_mov_b64 s[30:31], 0x80
	s_and_b32 s5, s11, 3
	s_add_i32 m0, s34, 0x18000
	v_lshl_add_u64 v[8:9], v[8:9], 0, s[30:31]
	s_lshl_b32 s92, s28, 6
	s_lshl_b32 s11, s28, 13
	s_lshl_b32 s50, s5, 12
	s_waitcnt vmcnt(2)
	s_barrier
	global_load_lds_dwordx4 v[8:9], off
	v_lshl_add_u64 v[6:7], v[6:7], 0, s[30:31]
	s_add_i32 m0, s34, 0x1a000
	s_add_i32 s95, s34, 0x8000
	s_add_i32 s97, s34, 0xa000
	global_load_lds_dwordx4 v[6:7], off
	v_lshl_add_u64 v[4:5], v[4:5], 0, s[30:31]
	s_mov_b32 m0, s95
	s_add_u32 s28, s8, 0x40080
	global_load_lds_dwordx4 v[4:5], off
	v_lshl_add_u64 v[4:5], v[10:11], 0, s[30:31]
	s_mov_b32 m0, s97
	s_addc_u32 s29, s9, 0
	global_load_lds_dwordx4 v[4:5], off
	s_add_i32 m0, s34, 0x1c000
	v_lshl_add_u64 v[4:5], s[28:29], 0, v[150:151]
	global_load_lds_dwordx4 v[4:5], off
	v_lshl_add_u64 v[4:5], s[28:29], 0, v[154:155]
	s_add_i32 m0, s34, 0x1e000
	v_and_b32_e32 v1, 15, v0
	global_load_lds_dwordx4 v[4:5], off
	v_lshlrev_b32_e32 v4, 1, v2
	v_lshlrev_b32_e32 v6, 2, v0
	v_lshl_or_b32 v5, v1, 6, v4
	v_and_b32_e32 v6, 32, v6
	v_bitop3_b32 v5, v5, s11, v6 bitop3:0xde
	v_lshlrev_b32_e32 v7, 6, v0
	s_movk_i32 s11, 0x3c0
	v_and_or_b32 v4, v7, s11, v4
	s_cmpk_lt_u32 s10, 0x100
	v_bitop3_b32 v147, s50, v4, v6 bitop3:0xf6
	s_cselect_b64 s[50:51], -1, 0
	s_ashr_i32 s10, s89, 31
	v_writelane_b32 v255, s10, 14
	s_and_b32 s10, s89, 7
	s_ashr_i32 s11, s89, 3
	s_mul_i32 s28, s10, 33
	s_and_b32 s29, s11, 7
	s_add_i32 s28, s29, s28
	v_writelane_b32 v255, s28, 15
	s_ashr_i32 s28, s89, 6
	v_writelane_b32 v255, s28, 16
	s_mul_i32 s28, s29, 33
	s_add_i32 s28, s28, 32
	s_and_b32 s11, s11, -8
	v_lshl_or_b32 v4, s5, 5, v2
	s_ashr_i32 s93, s33, 31
	v_writelane_b32 v255, s28, 17
	s_or_b32 s10, s11, s10
	v_or_b32_e32 v178, 0xfffff400, v4
	v_lshlrev_b32_e32 v4, 8, v0
	v_writelane_b32 v255, s10, 18
	s_add_u32 s10, s74, 0x3bc00000
	v_and_b32_e32 v4, 0x18000, v4
	v_lshlrev_b32_e32 v6, 11, v13
	s_addc_u32 s11, s75, 0
	v_or3_b32 v4, v3, v4, v6
	v_writelane_b32 v255, s10, 19
	v_add_u32_e32 v158, v4, v12
	v_lshlrev_b32_e32 v4, 4, v14
	v_writelane_b32 v255, s11, 20
	s_add_u32 s10, s74, 0x44000000
	v_and_b32_e32 v4, 0x38000, v4
	s_addc_u32 s11, s75, 0
	v_or3_b32 v3, v3, v4, v6
	v_writelane_b32 v255, s10, 21
	v_add_u32_e32 v160, v3, v12
	v_cndmask_b32_e64 v3, 0, 1, s[0:1]
	v_writelane_b32 v255, s11, 22
	v_cmp_ne_u32_e64 s[0:1], 1, v3
	s_waitcnt vmcnt(6)
	v_lshl_or_b32 v179, s5, 6, v2
	v_and_b32_e32 v237, 63, v0
	v_and_b32_e32 v238, 15, v237
	v_lshrrev_b32_e32 v239, 4, v237
	v_lshrrev_b32_e32 v240, 3, v237
	v_and_b32_e32 v241, 7, v237
	v_readfirstlane_b32 s100, v0
	s_nop 3
	s_lshr_b32 s100, s100, 6
	s_lshl_b32 s101, s100, 10
	s_add_i32 s101, s101, 0xc000
	v_and_b32_e32 v242, 7, v238
	v_lshrrev_b32_e32 v243, 3, v238
	v_lshlrev_b32_e32 v243, 13, v243
	v_lshl_add_u32 v243, v242, 7, v243
	v_add_u32_e32 v244, v239, v242
	v_and_b32_e32 v244, 7, v244
	v_lshl_add_u32 v232, v244, 4, v243
	v_add_u32_e32 v232, s101, v232
	v_add_u32_e32 v244, 4, v244
	v_and_b32_e32 v244, 7, v244
	v_lshl_add_u32 v233, v244, 4, v243
	v_add_u32_e32 v233, s101, v233
	v_add_u32_e32 v244, v241, v240
	v_and_b32_e32 v244, 7, v244
	v_lshlrev_b32_e32 v245, 7, v240
	v_lshl_add_u32 v234, v244, 4, v245
	v_add_u32_e32 v234, s101, v234
	s_mul_i32 s101, s100, 0x900
	s_add_i32 s101, s101, 0x21000
	v_mul_u32_u24_e32 v245, 0x90, v238
	v_lshl_add_u32 v235, v239, 5, v245
	v_add_u32_e32 v235, s101, v235
	v_mul_u32_u24_e32 v245, 0x90, v240
	v_lshl_add_u32 v236, v241, 4, v245
	v_add_u32_e32 v236, s101, v236
	v_sub_u32_e32 v245, v240, v238
	v_lshlrev_b32_e32 v245, 11, v245
	v_sub_u32_e32 v244, v241, v239
	v_lshl_add_u32 v250, v244, 4, v245
	v_ashrrev_i32_e32 v251, 31, v250
	v_lshlrev_b32_e32 v245, 1, v245
	v_lshl_add_u32 v252, v241, 4, v245
	v_lshlrev_b32_e32 v244, 5, v239
	v_sub_u32_e32 v252, v252, v244
	v_ashrrev_i32_e32 v253, 31, v252
	s_movk_i32 s98, 0x4000
	s_mov_b32 s99, 0
	s_mov_b32 s100, 0x8000
	s_mov_b32 s101, 0
	s_add_i32 s57, 0, 0x10000
	v_writelane_b32 v255, s0, 23
	s_add_i32 s60, 0, 0x14000
	v_lshlrev_b32_e32 v183, 2, v2
	v_writelane_b32 v255, s1, 24
	v_mbcnt_lo_u32_b32 v2, -1, 0
	v_mov_b32_e32 v159, v157
	v_mov_b32_e32 v161, v157
	v_add_u32_e32 v180, s57, v147
	v_add_u32_e32 v181, s60, v147
	v_add_u32_e32 v182, 0, v5
	v_mov_b32_e32 v184, 0x358637bd
	s_mov_b32 s61, 0xf800000
	v_mov_b32_e32 v185, 0x260
	v_mov_b64_e32 v[162:163], 0x20ff
	v_mov_b32_e32 v186, 0x3e38aa3b
	v_mbcnt_hi_u32_b32 v187, -1, v2
	v_writelane_b32 v255, s14, 25
	s_barrier
	s_branch .LBB0_117

; #define GAS __attribute__((address_space(1)))
;     __device__ __forceinline__ bool operator()(pg8::f32x4 (&acc)[2][2][4][2], const pg8::Unit& u, int wr, int wc, int fr, int fq) const {
;     ...
;                     } else if (g == 4) {
;                         GAS f32x4* o = (GAS f32x4*)(vout + row * DM + cb + bj * 32); o[0] = (f32x4){v[0], v[1], v[2], v[3]}; o[1] = (f32x4){v[4], v[5], v[6], v[7]};
.LBB0_137:
	ds_write_b128 v235, v[126:129]
	ds_write_b128 v235, v[122:125] offset:16
	ds_read_b128 v[238:241], v236
	ds_read_b128 v[242:245], v236 offset:1152
	v_lshl_add_u64 v[246:247], v[136:137], 0, v[252:253]
	v_lshl_add_u64 v[248:249], v[246:247], 0, s[100:101]
	s_waitcnt lgkmcnt(0)
	global_store_dwordx4 v[246:247], v[238:241], off
	global_store_dwordx4 v[248:249], v[242:245], off

; #define GAS __attribute__((address_space(1)))
; __device__ __forceinline__ float sigm(float v) { return __builtin_amdgcn_rcpf(1.f + __builtin_amdgcn_exp2f(-LOG2E * v)); }
; __device__ __forceinline__ v4u pack8(const float* v) { v4u w; w.x = pk2(v[0], v[1]); w.y = pk2(v[2], v[3]); w.z = pk2(v[4], v[5]); w.w = pk2(v[6], v[7]); return w; }
;     __device__ __forceinline__ bool operator()(pg8::f32x4 (&acc)[2][2][4][2], const pg8::Unit& u, int wr, int wc, int fr, int fq) const {
;     ...
;                     if (g == 0) {
;                         const int t = smp ? (rowi & 63) : (rowi & 2047); const int T = smp ? 64 : 2048;
;                         if (t >= T - 3) { const int b = smp ? ((rowi - MP) >> 6) : (rowi >> 11);
;                             GAS f32x4* o = (GAS f32x4*)(out + (smp ? O_CS : O_CP) + (size_t)(b * 3 + (t - (T - 3))) * DM + cb + bj * 32);
;                             o[0] = (f32x4){v[0], v[1], v[2], v[3]}; o[1] = (f32x4){v[4], v[5], v[6], v[7]}; }
;                     } else if (g == 4) {
;                         GAS f32x4* o = (GAS f32x4*)(vout + row * DM + cb + bj * 32); o[0] = (f32x4){v[0], v[1], v[2], v[3]}; o[1] = (f32x4){v[4], v[5], v[6], v[7]};
;                     } else if (g == 1 || g == 5) {
; #pragma unroll
;                         for (int e = 0; e < 8; ++e) v[e] = v[e] * sigm(v[e]);
;                     } else if (g == 6 || g == 7) {
; #pragma unroll
;                         for (int e = 0; e < 8; ++e) v[e] = sigm(v[e]);
;                     }
;                     *(GAS v4u*)(dstb + row * DM + cb + bj * 32) = pack8(v);
.LBB0_143:
	s_and_b64 s[90:91], s[90:91], exec
	s_mov_b32 s90, 0x2b400000
	s_cselect_b32 s90, s90, 0x33800000
	s_cmp_lg_u32 s29, 1
	s_cselect_b32 s90, s90, 0x12800000
	s_and_b64 s[8:9], s[8:9], exec
	s_cselect_b32 s8, 0xa400000, s90
	s_add_u32 s8, s74, s8
	s_addc_u32 s9, s75, 0
	v_lshlrev_b32_e32 v156, 1, v172
	v_cndmask_b32_e64 v131, 0, 1, s[6:7]
	v_lshl_add_u64 v[134:135], s[8:9], 0, v[156:157]
	v_lshlrev_b64 v[140:141], 11, v[164:165]
	v_cmp_ne_u32_e64 s[8:9], 1, v131
	v_cndmask_b32_e64 v131, 0, 1, s[88:89]
	v_lshl_add_u64 v[140:141], v[134:135], 0, v[140:141]
	v_cvt_pk_bf16_f32 v168, v168, v169
	v_cvt_pk_bf16_f32 v169, v144, v145
	s_mov_b64 s[90:91], -1
	s_andn2_b64 vcc, exec, s[6:7]
	v_cmp_ne_u32_e64 s[6:7], 1, v131
	v_cvt_pk_bf16_f32 v170, v166, v167
	v_cvt_pk_bf16_f32 v171, v142, v143
	ds_write_b128 v232, v[168:171]
	s_cbranch_vccnz .LBB0_150
	s_and_b64 vcc, exec, s[6:7]
	s_cbranch_vccnz .LBB0_147
	s_andn2_b64 vcc, exec, s[86:87]
	s_cbranch_vccnz .LBB0_349
	v_mul_f32_e32 v131, 0xbfb8aa3b, v118
	v_exp_f32_e32 v131, v131
	v_mul_f32_e32 v142, 0xbfb8aa3b, v119
	v_mul_f32_e32 v143, 0xbfb8aa3b, v120
	v_exp_f32_e32 v144, v142
	v_exp_f32_e32 v145, v143
	v_add_f32_e32 v131, 1.0, v131
	v_rcp_f32_e32 v142, v131
	v_add_f32_e32 v131, 1.0, v144
	v_mul_f32_e32 v144, 0xbfb8aa3b, v121
	v_rcp_f32_e32 v143, v131
	v_add_f32_e32 v131, 1.0, v145
	v_exp_f32_e32 v145, v144
	v_mul_f32_e32 v144, 0xbfb8aa3b, v114
	v_exp_f32_e32 v156, v144
	v_rcp_f32_e32 v144, v131
	v_add_f32_e32 v131, 1.0, v145
	v_rcp_f32_e32 v145, v131
	v_add_f32_e32 v131, 1.0, v156
	v_mul_f32_e32 v156, 0xbfb8aa3b, v116
	v_rcp_f32_e32 v166, v131
	v_mul_f32_e32 v131, 0xbfb8aa3b, v115
	v_exp_f32_e32 v156, v156
	v_mul_f32_e32 v165, 0xbfb8aa3b, v117
	v_exp_f32_e32 v131, v131
	v_exp_f32_e32 v165, v165
	v_add_f32_e32 v156, 1.0, v156
	v_rcp_f32_e32 v170, v156
	v_add_f32_e32 v131, 1.0, v131
	v_add_f32_e32 v156, 1.0, v165
	v_rcp_f32_e32 v171, v156
	v_rcp_f32_e32 v167, v131
	v_pk_mul_f32 v[144:145], v[120:121], v[144:145]
	v_pk_mul_f32 v[168:169], v[118:119], v[142:143]
	v_pk_mul_f32 v[142:143], v[116:117], v[170:171]
	v_pk_mul_f32 v[166:167], v[114:115], v[166:167]
	s_cbranch_execz .LBB0_148
	s_branch .LBB0_149

; #define GAS __attribute__((address_space(1)))
;     __device__ __forceinline__ bool operator()(pg8::f32x4 (&acc)[2][2][4][2], const pg8::Unit& u, int wr, int wc, int fr, int fq) const {
;     ...
;                     } else if (g == 4) {
;                         GAS f32x4* o = (GAS f32x4*)(vout + row * DM + cb + bj * 32); o[0] = (f32x4){v[0], v[1], v[2], v[3]}; o[1] = (f32x4){v[4], v[5], v[6], v[7]};
.LBB0_148:
	ds_write_b128 v235, v[118:121]
	ds_write_b128 v235, v[114:117] offset:16
	ds_read_b128 v[238:241], v236
	ds_read_b128 v[242:245], v236 offset:1152
	v_lshl_add_u64 v[246:247], v[136:137], 0, v[252:253]
	v_lshl_add_u64 v[248:249], v[246:247], 0, s[100:101]
	s_waitcnt lgkmcnt(0)
	global_store_dwordx4 v[246:247], v[238:241], off offset:128
	global_store_dwordx4 v[248:249], v[242:245], off offset:128

; #define GAS __attribute__((address_space(1)))
; __device__ __forceinline__ float sigm(float v) { return __builtin_amdgcn_rcpf(1.f + __builtin_amdgcn_exp2f(-LOG2E * v)); }
; __device__ __forceinline__ v4u pack8(const float* v) { v4u w; w.x = pk2(v[0], v[1]); w.y = pk2(v[2], v[3]); w.z = pk2(v[4], v[5]); w.w = pk2(v[6], v[7]); return w; }
;     __device__ __forceinline__ bool operator()(pg8::f32x4 (&acc)[2][2][4][2], const pg8::Unit& u, int wr, int wc, int fr, int fq) const {
;     ...
; #pragma unroll
;         for (int ai = 0; ai < 2; ++ai)
; #pragma unroll
;             for (int m = 0; m < 4; ++m) {
;                 const int rowi = row0 + ai * 128 + m * 16; const size_t row = (size_t)rowi;
; #pragma unroll
;                 for (int bj = 0; bj < 2; ++bj) {
;                     float v[8];
; #pragma unroll
;                     for (int e = 0; e < 8; ++e) v[e] = acc[ai][bj][m][e >> 2][e & 3];
;                     if (g == 0) {
;                         const int t = smp ? (rowi & 63) : (rowi & 2047); const int T = smp ? 64 : 2048;
;                         if (t >= T - 3) { const int b = smp ? ((rowi - MP) >> 6) : (rowi >> 11);
;                             GAS f32x4* o = (GAS f32x4*)(out + (smp ? O_CS : O_CP) + (size_t)(b * 3 + (t - (T - 3))) * DM + cb + bj * 32);
;                             o[0] = (f32x4){v[0], v[1], v[2], v[3]}; o[1] = (f32x4){v[4], v[5], v[6], v[7]}; }
;                     } else if (g == 4) {
;                         GAS f32x4* o = (GAS f32x4*)(vout + row * DM + cb + bj * 32); o[0] = (f32x4){v[0], v[1], v[2], v[3]}; o[1] = (f32x4){v[4], v[5], v[6], v[7]};
;                     } else if (g == 1 || g == 5) {
; #pragma unroll
;                         for (int e = 0; e < 8; ++e) v[e] = v[e] * sigm(v[e]);
;                     } else if (g == 6 || g == 7) {
; #pragma unroll
;                         for (int e = 0; e < 8; ++e) v[e] = sigm(v[e]);
;                     }
;                     *(GAS v4u*)(dstb + row * DM + cb + bj * 32) = pack8(v);
.LBB0_154:
	v_cvt_pk_bf16_f32 v136, v168, v169
	v_cvt_pk_bf16_f32 v137, v144, v145
	v_cvt_pk_bf16_f32 v138, v166, v167
	v_cvt_pk_bf16_f32 v139, v142, v143
	ds_write_b128 v233, v[136:139]
	ds_read_b128 v[238:241], v234
	ds_read_b128 v[242:245], v234 offset:8192
	v_lshl_add_u64 v[246:247], v[140:141], 0, v[250:251]
	v_lshl_add_u64 v[248:249], v[246:247], 0, s[98:99]
	s_waitcnt lgkmcnt(0)
	global_store_dwordx4 v[246:247], v[238:241], off
	global_store_dwordx4 v[248:249], v[242:245], off
	v_or_b32_e32 v140, 16, v164
	v_ashrrev_i32_e32 v141, 31, v140
	v_lshlrev_b64 v[136:137], 12, v[140:141]
	v_bitop3_b32 v131, v164, s71, 16 bitop3:0xc8
	v_lshl_add_u64 v[136:137], v[132:133], 0, v[136:137]
	v_cmp_le_u32_e64 s[10:11], s76, v131
	s_and_b64 vcc, exec, s[8:9]
	s_mov_b64 s[88:89], -1
	s_cbranch_vccnz .LBB0_161
	s_and_b64 vcc, exec, s[6:7]
	s_cbranch_vccnz .LBB0_158
	s_andn2_b64 vcc, exec, s[86:87]
	s_cbranch_vccnz .LBB0_350
	v_mul_f32_e32 v144, 0xbfb8aa3b, v106
	v_exp_f32_e32 v144, v144
	v_mul_f32_e32 v145, 0xbfb8aa3b, v108
	v_mul_f32_e32 v138, 0xbfb8aa3b, v110
	v_mul_f32_e32 v139, 0xbfb8aa3b, v111
	v_add_f32_e32 v144, 1.0, v144
	v_mul_f32_e32 v142, 0xbfb8aa3b, v112
	v_mul_f32_e32 v143, 0xbfb8aa3b, v113
	v_rcp_f32_e32 v166, v144
	v_mul_f32_e32 v144, 0xbfb8aa3b, v107
	v_exp_f32_e32 v145, v145
	v_mul_f32_e32 v156, 0xbfb8aa3b, v109
	v_exp_f32_e32 v138, v138
	v_exp_f32_e32 v139, v139
	v_exp_f32_e32 v142, v142
	v_exp_f32_e32 v143, v143
	v_exp_f32_e32 v144, v144
	v_exp_f32_e32 v156, v156
	v_add_f32_e32 v145, 1.0, v145
	v_add_f32_e32 v138, 1.0, v138
	v_add_f32_e32 v139, 1.0, v139
	v_add_f32_e32 v142, 1.0, v142
	v_add_f32_e32 v143, 1.0, v143
	v_add_f32_e32 v144, 1.0, v144
	v_rcp_f32_e32 v170, v145
	v_add_f32_e32 v145, 1.0, v156
	v_rcp_f32_e32 v138, v138
	v_rcp_f32_e32 v139, v139
	v_rcp_f32_e32 v142, v142
	v_rcp_f32_e32 v143, v143
	v_rcp_f32_e32 v171, v145
	v_rcp_f32_e32 v167, v144
	v_pk_mul_f32 v[168:169], v[110:111], v[138:139]
	v_pk_mul_f32 v[144:145], v[112:113], v[142:143]
	v_pk_mul_f32 v[142:143], v[108:109], v[170:171]
	v_pk_mul_f32 v[166:167], v[106:107], v[166:167]
	s_cbranch_execz .LBB0_159
	s_branch .LBB0_160

; #define GAS __attribute__((address_space(1)))
;     __device__ __forceinline__ bool operator()(pg8::f32x4 (&acc)[2][2][4][2], const pg8::Unit& u, int wr, int wc, int fr, int fq) const {
;     ...
;                     } else if (g == 4) {
;                         GAS f32x4* o = (GAS f32x4*)(vout + row * DM + cb + bj * 32); o[0] = (f32x4){v[0], v[1], v[2], v[3]}; o[1] = (f32x4){v[4], v[5], v[6], v[7]};
.LBB0_159:
	ds_write_b128 v235, v[110:113]
	ds_write_b128 v235, v[106:109] offset:16
	ds_read_b128 v[238:241], v236
	ds_read_b128 v[242:245], v236 offset:1152
	v_lshl_add_u64 v[246:247], v[136:137], 0, v[252:253]
	v_lshl_add_u64 v[248:249], v[246:247], 0, s[100:101]
	s_waitcnt lgkmcnt(0)
	global_store_dwordx4 v[246:247], v[238:241], off
	global_store_dwordx4 v[248:249], v[242:245], off

; #define GAS __attribute__((address_space(1)))
; __device__ __forceinline__ float sigm(float v) { return __builtin_amdgcn_rcpf(1.f + __builtin_amdgcn_exp2f(-LOG2E * v)); }
; __device__ __forceinline__ v4u pack8(const float* v) { v4u w; w.x = pk2(v[0], v[1]); w.y = pk2(v[2], v[3]); w.z = pk2(v[4], v[5]); w.w = pk2(v[6], v[7]); return w; }
;     __device__ __forceinline__ bool operator()(pg8::f32x4 (&acc)[2][2][4][2], const pg8::Unit& u, int wr, int wc, int fr, int fq) const {
;     ...
;                     if (g == 0) {
;                         const int t = smp ? (rowi & 63) : (rowi & 2047); const int T = smp ? 64 : 2048;
;                         if (t >= T - 3) { const int b = smp ? ((rowi - MP) >> 6) : (rowi >> 11);
;                             GAS f32x4* o = (GAS f32x4*)(out + (smp ? O_CS : O_CP) + (size_t)(b * 3 + (t - (T - 3))) * DM + cb + bj * 32);
;                             o[0] = (f32x4){v[0], v[1], v[2], v[3]}; o[1] = (f32x4){v[4], v[5], v[6], v[7]}; }
;                     } else if (g == 4) {
;                         GAS f32x4* o = (GAS f32x4*)(vout + row * DM + cb + bj * 32); o[0] = (f32x4){v[0], v[1], v[2], v[3]}; o[1] = (f32x4){v[4], v[5], v[6], v[7]};
;                     } else if (g == 1 || g == 5) {
; #pragma unroll
;                         for (int e = 0; e < 8; ++e) v[e] = v[e] * sigm(v[e]);
;                     } else if (g == 6 || g == 7) {
; #pragma unroll
;                         for (int e = 0; e < 8; ++e) v[e] = sigm(v[e]);
;                     }
;                     *(GAS v4u*)(dstb + row * DM + cb + bj * 32) = pack8(v);
.LBB0_165:
	v_lshlrev_b64 v[140:141], 11, v[140:141]
	v_lshl_add_u64 v[140:141], v[134:135], 0, v[140:141]
	v_cvt_pk_bf16_f32 v168, v168, v169
	v_cvt_pk_bf16_f32 v169, v144, v145
	s_and_b64 vcc, exec, s[8:9]
	s_mov_b64 s[88:89], -1
	v_cvt_pk_bf16_f32 v170, v166, v167
	v_cvt_pk_bf16_f32 v171, v142, v143
	ds_write_b128 v232, v[168:171]
	s_cbranch_vccnz .LBB0_172
	s_and_b64 vcc, exec, s[6:7]
	s_cbranch_vccnz .LBB0_169
	s_andn2_b64 vcc, exec, s[86:87]
	s_cbranch_vccnz .LBB0_351
	v_mul_f32_e32 v131, 0xbfb8aa3b, v102
	v_exp_f32_e32 v131, v131
	v_mul_f32_e32 v142, 0xbfb8aa3b, v103
	v_mul_f32_e32 v143, 0xbfb8aa3b, v104
	v_exp_f32_e32 v144, v142
	v_exp_f32_e32 v145, v143
	v_add_f32_e32 v131, 1.0, v131
	v_rcp_f32_e32 v142, v131
	v_add_f32_e32 v131, 1.0, v144
	v_mul_f32_e32 v144, 0xbfb8aa3b, v105
	v_rcp_f32_e32 v143, v131
	v_add_f32_e32 v131, 1.0, v145
	v_exp_f32_e32 v145, v144
	v_mul_f32_e32 v144, 0xbfb8aa3b, v98
	v_exp_f32_e32 v156, v144
	v_rcp_f32_e32 v144, v131
	v_add_f32_e32 v131, 1.0, v145
	v_rcp_f32_e32 v145, v131
	v_add_f32_e32 v131, 1.0, v156
	v_mul_f32_e32 v156, 0xbfb8aa3b, v100
	v_rcp_f32_e32 v166, v131
	v_mul_f32_e32 v131, 0xbfb8aa3b, v99
	v_exp_f32_e32 v156, v156
	v_mul_f32_e32 v165, 0xbfb8aa3b, v101
	v_exp_f32_e32 v131, v131
	v_exp_f32_e32 v165, v165
	v_add_f32_e32 v156, 1.0, v156
	v_rcp_f32_e32 v170, v156
	v_add_f32_e32 v131, 1.0, v131
	v_add_f32_e32 v156, 1.0, v165
	v_rcp_f32_e32 v171, v156
	v_rcp_f32_e32 v167, v131
	v_pk_mul_f32 v[144:145], v[104:105], v[144:145]
	v_pk_mul_f32 v[168:169], v[102:103], v[142:143]
	v_pk_mul_f32 v[142:143], v[100:101], v[170:171]
	v_pk_mul_f32 v[166:167], v[98:99], v[166:167]
	s_cbranch_execz .LBB0_170
	s_branch .LBB0_171

; #define GAS __attribute__((address_space(1)))
;     __device__ __forceinline__ bool operator()(pg8::f32x4 (&acc)[2][2][4][2], const pg8::Unit& u, int wr, int wc, int fr, int fq) const {
;     ...
;                     } else if (g == 4) {
;                         GAS f32x4* o = (GAS f32x4*)(vout + row * DM + cb + bj * 32); o[0] = (f32x4){v[0], v[1], v[2], v[3]}; o[1] = (f32x4){v[4], v[5], v[6], v[7]};
.LBB0_170:
	ds_write_b128 v235, v[102:105]
	ds_write_b128 v235, v[98:101] offset:16
	ds_read_b128 v[238:241], v236
	ds_read_b128 v[242:245], v236 offset:1152
	v_lshl_add_u64 v[246:247], v[136:137], 0, v[252:253]
	v_lshl_add_u64 v[248:249], v[246:247], 0, s[100:101]
	s_waitcnt lgkmcnt(0)
	global_store_dwordx4 v[246:247], v[238:241], off offset:128
	global_store_dwordx4 v[248:249], v[242:245], off offset:128

; #define GAS __attribute__((address_space(1)))
; __device__ __forceinline__ float sigm(float v) { return __builtin_amdgcn_rcpf(1.f + __builtin_amdgcn_exp2f(-LOG2E * v)); }
; __device__ __forceinline__ v4u pack8(const float* v) { v4u w; w.x = pk2(v[0], v[1]); w.y = pk2(v[2], v[3]); w.z = pk2(v[4], v[5]); w.w = pk2(v[6], v[7]); return w; }
;     __device__ __forceinline__ bool operator()(pg8::f32x4 (&acc)[2][2][4][2], const pg8::Unit& u, int wr, int wc, int fr, int fq) const {
;     ...
; #pragma unroll
;         for (int ai = 0; ai < 2; ++ai)
; #pragma unroll
;             for (int m = 0; m < 4; ++m) {
;                 const int rowi = row0 + ai * 128 + m * 16; const size_t row = (size_t)rowi;
; #pragma unroll
;                 for (int bj = 0; bj < 2; ++bj) {
;                     float v[8];
; #pragma unroll
;                     for (int e = 0; e < 8; ++e) v[e] = acc[ai][bj][m][e >> 2][e & 3];
;                     if (g == 0) {
;                         const int t = smp ? (rowi & 63) : (rowi & 2047); const int T = smp ? 64 : 2048;
;                         if (t >= T - 3) { const int b = smp ? ((rowi - MP) >> 6) : (rowi >> 11);
;                             GAS f32x4* o = (GAS f32x4*)(out + (smp ? O_CS : O_CP) + (size_t)(b * 3 + (t - (T - 3))) * DM + cb + bj * 32);
;                             o[0] = (f32x4){v[0], v[1], v[2], v[3]}; o[1] = (f32x4){v[4], v[5], v[6], v[7]}; }
;                     } else if (g == 4) {
;                         GAS f32x4* o = (GAS f32x4*)(vout + row * DM + cb + bj * 32); o[0] = (f32x4){v[0], v[1], v[2], v[3]}; o[1] = (f32x4){v[4], v[5], v[6], v[7]};
;                     } else if (g == 1 || g == 5) {
; #pragma unroll
;                         for (int e = 0; e < 8; ++e) v[e] = v[e] * sigm(v[e]);
;                     } else if (g == 6 || g == 7) {
; #pragma unroll
;                         for (int e = 0; e < 8; ++e) v[e] = sigm(v[e]);
;                     }
;                     *(GAS v4u*)(dstb + row * DM + cb + bj * 32) = pack8(v);
.LBB0_176:
	v_cvt_pk_bf16_f32 v136, v168, v169
	v_cvt_pk_bf16_f32 v137, v144, v145
	v_cvt_pk_bf16_f32 v138, v166, v167
	v_cvt_pk_bf16_f32 v139, v142, v143
	ds_write_b128 v233, v[136:139]
	ds_read_b128 v[238:241], v234
	ds_read_b128 v[242:245], v234 offset:8192
	v_lshl_add_u64 v[246:247], v[140:141], 0, v[250:251]
	v_lshl_add_u64 v[248:249], v[246:247], 0, s[98:99]
	s_waitcnt lgkmcnt(0)
	global_store_dwordx4 v[246:247], v[238:241], off
	global_store_dwordx4 v[248:249], v[242:245], off
	v_or_b32_e32 v140, 32, v164
	v_ashrrev_i32_e32 v141, 31, v140
	v_lshlrev_b64 v[136:137], 12, v[140:141]
	v_bitop3_b32 v131, v164, s71, 32 bitop3:0xc8
	v_lshl_add_u64 v[136:137], v[132:133], 0, v[136:137]
	v_cmp_le_u32_e64 s[10:11], s76, v131
	s_and_b64 vcc, exec, s[8:9]
	s_mov_b64 s[88:89], -1
	s_cbranch_vccnz .LBB0_183
	s_and_b64 vcc, exec, s[6:7]
	s_cbranch_vccnz .LBB0_180
	s_andn2_b64 vcc, exec, s[86:87]
	s_cbranch_vccnz .LBB0_352
	v_mul_f32_e32 v144, 0xbfb8aa3b, v90
	v_exp_f32_e32 v144, v144
	v_mul_f32_e32 v145, 0xbfb8aa3b, v92
	v_mul_f32_e32 v138, 0xbfb8aa3b, v94
	v_mul_f32_e32 v139, 0xbfb8aa3b, v95
	v_add_f32_e32 v144, 1.0, v144
	v_mul_f32_e32 v142, 0xbfb8aa3b, v96
	v_mul_f32_e32 v143, 0xbfb8aa3b, v97
	v_rcp_f32_e32 v166, v144
	v_mul_f32_e32 v144, 0xbfb8aa3b, v91
	v_exp_f32_e32 v145, v145
	v_mul_f32_e32 v156, 0xbfb8aa3b, v93
	v_exp_f32_e32 v138, v138
	v_exp_f32_e32 v139, v139
	v_exp_f32_e32 v142, v142
	v_exp_f32_e32 v143, v143
	v_exp_f32_e32 v144, v144
	v_exp_f32_e32 v156, v156
	v_add_f32_e32 v145, 1.0, v145
	v_add_f32_e32 v138, 1.0, v138
	v_add_f32_e32 v139, 1.0, v139
	v_add_f32_e32 v142, 1.0, v142
	v_add_f32_e32 v143, 1.0, v143
	v_add_f32_e32 v144, 1.0, v144
	v_rcp_f32_e32 v170, v145
	v_add_f32_e32 v145, 1.0, v156
	v_rcp_f32_e32 v138, v138
	v_rcp_f32_e32 v139, v139
	v_rcp_f32_e32 v142, v142
	v_rcp_f32_e32 v143, v143
	v_rcp_f32_e32 v171, v145
	v_rcp_f32_e32 v167, v144
	v_pk_mul_f32 v[168:169], v[94:95], v[138:139]
	v_pk_mul_f32 v[144:145], v[96:97], v[142:143]
	v_pk_mul_f32 v[142:143], v[92:93], v[170:171]
	v_pk_mul_f32 v[166:167], v[90:91], v[166:167]
	s_cbranch_execz .LBB0_181
	s_branch .LBB0_182

; #define GAS __attribute__((address_space(1)))
;     __device__ __forceinline__ bool operator()(pg8::f32x4 (&acc)[2][2][4][2], const pg8::Unit& u, int wr, int wc, int fr, int fq) const {
;     ...
;                     } else if (g == 4) {
;                         GAS f32x4* o = (GAS f32x4*)(vout + row * DM + cb + bj * 32); o[0] = (f32x4){v[0], v[1], v[2], v[3]}; o[1] = (f32x4){v[4], v[5], v[6], v[7]};
.LBB0_181:
	ds_write_b128 v235, v[94:97]
	ds_write_b128 v235, v[90:93] offset:16
	ds_read_b128 v[238:241], v236
	ds_read_b128 v[242:245], v236 offset:1152
	v_lshl_add_u64 v[246:247], v[136:137], 0, v[252:253]
	v_lshl_add_u64 v[248:249], v[246:247], 0, s[100:101]
	s_waitcnt lgkmcnt(0)
	global_store_dwordx4 v[246:247], v[238:241], off
	global_store_dwordx4 v[248:249], v[242:245], off

; #define GAS __attribute__((address_space(1)))
; __device__ __forceinline__ float sigm(float v) { return __builtin_amdgcn_rcpf(1.f + __builtin_amdgcn_exp2f(-LOG2E * v)); }
; __device__ __forceinline__ v4u pack8(const float* v) { v4u w; w.x = pk2(v[0], v[1]); w.y = pk2(v[2], v[3]); w.z = pk2(v[4], v[5]); w.w = pk2(v[6], v[7]); return w; }
;     __device__ __forceinline__ bool operator()(pg8::f32x4 (&acc)[2][2][4][2], const pg8::Unit& u, int wr, int wc, int fr, int fq) const {
;     ...
;                     if (g == 0) {
;                         const int t = smp ? (rowi & 63) : (rowi & 2047); const int T = smp ? 64 : 2048;
;                         if (t >= T - 3) { const int b = smp ? ((rowi - MP) >> 6) : (rowi >> 11);
;                             GAS f32x4* o = (GAS f32x4*)(out + (smp ? O_CS : O_CP) + (size_t)(b * 3 + (t - (T - 3))) * DM + cb + bj * 32);
;                             o[0] = (f32x4){v[0], v[1], v[2], v[3]}; o[1] = (f32x4){v[4], v[5], v[6], v[7]}; }
;                     } else if (g == 4) {
;                         GAS f32x4* o = (GAS f32x4*)(vout + row * DM + cb + bj * 32); o[0] = (f32x4){v[0], v[1], v[2], v[3]}; o[1] = (f32x4){v[4], v[5], v[6], v[7]};
;                     } else if (g == 1 || g == 5) {
; #pragma unroll
;                         for (int e = 0; e < 8; ++e) v[e] = v[e] * sigm(v[e]);
;                     } else if (g == 6 || g == 7) {
; #pragma unroll
;                         for (int e = 0; e < 8; ++e) v[e] = sigm(v[e]);
;                     }
;                     *(GAS v4u*)(dstb + row * DM + cb + bj * 32) = pack8(v);
.LBB0_187:
	v_lshlrev_b64 v[140:141], 11, v[140:141]
	v_lshl_add_u64 v[140:141], v[134:135], 0, v[140:141]
	v_cvt_pk_bf16_f32 v168, v168, v169
	v_cvt_pk_bf16_f32 v169, v144, v145
	s_and_b64 vcc, exec, s[8:9]
	s_mov_b64 s[88:89], -1
	v_cvt_pk_bf16_f32 v170, v166, v167
	v_cvt_pk_bf16_f32 v171, v142, v143
	ds_write_b128 v232, v[168:171]
	s_cbranch_vccnz .LBB0_194
	s_and_b64 vcc, exec, s[6:7]
	s_cbranch_vccnz .LBB0_191
	s_andn2_b64 vcc, exec, s[86:87]
	s_cbranch_vccnz .LBB0_353
	v_mul_f32_e32 v131, 0xbfb8aa3b, v86
	v_exp_f32_e32 v131, v131
	v_mul_f32_e32 v142, 0xbfb8aa3b, v87
	v_mul_f32_e32 v143, 0xbfb8aa3b, v88
	v_exp_f32_e32 v144, v142
	v_exp_f32_e32 v145, v143
	v_add_f32_e32 v131, 1.0, v131
	v_rcp_f32_e32 v142, v131
	v_add_f32_e32 v131, 1.0, v144
	v_mul_f32_e32 v144, 0xbfb8aa3b, v89
	v_rcp_f32_e32 v143, v131
	v_add_f32_e32 v131, 1.0, v145
	v_exp_f32_e32 v145, v144
	v_mul_f32_e32 v144, 0xbfb8aa3b, v82
	v_exp_f32_e32 v156, v144
	v_rcp_f32_e32 v144, v131
	v_add_f32_e32 v131, 1.0, v145
	v_rcp_f32_e32 v145, v131
	v_add_f32_e32 v131, 1.0, v156
	v_mul_f32_e32 v156, 0xbfb8aa3b, v84
	v_rcp_f32_e32 v166, v131
	v_mul_f32_e32 v131, 0xbfb8aa3b, v83
	v_exp_f32_e32 v156, v156
	v_mul_f32_e32 v165, 0xbfb8aa3b, v85
	v_exp_f32_e32 v131, v131
	v_exp_f32_e32 v165, v165
	v_add_f32_e32 v156, 1.0, v156
	v_rcp_f32_e32 v170, v156
	v_add_f32_e32 v131, 1.0, v131
	v_add_f32_e32 v156, 1.0, v165
	v_rcp_f32_e32 v171, v156
	v_rcp_f32_e32 v167, v131
	v_pk_mul_f32 v[144:145], v[88:89], v[144:145]
	v_pk_mul_f32 v[168:169], v[86:87], v[142:143]
	v_pk_mul_f32 v[142:143], v[84:85], v[170:171]
	v_pk_mul_f32 v[166:167], v[82:83], v[166:167]
	s_cbranch_execz .LBB0_192
	s_branch .LBB0_193

; #define GAS __attribute__((address_space(1)))
;     __device__ __forceinline__ bool operator()(pg8::f32x4 (&acc)[2][2][4][2], const pg8::Unit& u, int wr, int wc, int fr, int fq) const {
;     ...
;                     } else if (g == 4) {
;                         GAS f32x4* o = (GAS f32x4*)(vout + row * DM + cb + bj * 32); o[0] = (f32x4){v[0], v[1], v[2], v[3]}; o[1] = (f32x4){v[4], v[5], v[6], v[7]};
.LBB0_192:
	ds_write_b128 v235, v[86:89]
	ds_write_b128 v235, v[82:85] offset:16
	ds_read_b128 v[238:241], v236
	ds_read_b128 v[242:245], v236 offset:1152
	v_lshl_add_u64 v[246:247], v[136:137], 0, v[252:253]
	v_lshl_add_u64 v[248:249], v[246:247], 0, s[100:101]
	s_waitcnt lgkmcnt(0)
	global_store_dwordx4 v[246:247], v[238:241], off offset:128
	global_store_dwordx4 v[248:249], v[242:245], off offset:128

; #define GAS __attribute__((address_space(1)))
; __device__ __forceinline__ float sigm(float v) { return __builtin_amdgcn_rcpf(1.f + __builtin_amdgcn_exp2f(-LOG2E * v)); }
; __device__ __forceinline__ v4u pack8(const float* v) { v4u w; w.x = pk2(v[0], v[1]); w.y = pk2(v[2], v[3]); w.z = pk2(v[4], v[5]); w.w = pk2(v[6], v[7]); return w; }
;     __device__ __forceinline__ bool operator()(pg8::f32x4 (&acc)[2][2][4][2], const pg8::Unit& u, int wr, int wc, int fr, int fq) const {
;     ...
; #pragma unroll
;         for (int ai = 0; ai < 2; ++ai)
; #pragma unroll
;             for (int m = 0; m < 4; ++m) {
;                 const int rowi = row0 + ai * 128 + m * 16; const size_t row = (size_t)rowi;
; #pragma unroll
;                 for (int bj = 0; bj < 2; ++bj) {
;                     float v[8];
; #pragma unroll
;                     for (int e = 0; e < 8; ++e) v[e] = acc[ai][bj][m][e >> 2][e & 3];
;                     if (g == 0) {
;                         const int t = smp ? (rowi & 63) : (rowi & 2047); const int T = smp ? 64 : 2048;
;                         if (t >= T - 3) { const int b = smp ? ((rowi - MP) >> 6) : (rowi >> 11);
;                             GAS f32x4* o = (GAS f32x4*)(out + (smp ? O_CS : O_CP) + (size_t)(b * 3 + (t - (T - 3))) * DM + cb + bj * 32);
;                             o[0] = (f32x4){v[0], v[1], v[2], v[3]}; o[1] = (f32x4){v[4], v[5], v[6], v[7]}; }
;                     } else if (g == 4) {
;                         GAS f32x4* o = (GAS f32x4*)(vout + row * DM + cb + bj * 32); o[0] = (f32x4){v[0], v[1], v[2], v[3]}; o[1] = (f32x4){v[4], v[5], v[6], v[7]};
;                     } else if (g == 1 || g == 5) {
; #pragma unroll
;                         for (int e = 0; e < 8; ++e) v[e] = v[e] * sigm(v[e]);
;                     } else if (g == 6 || g == 7) {
; #pragma unroll
;                         for (int e = 0; e < 8; ++e) v[e] = sigm(v[e]);
;                     }
;                     *(GAS v4u*)(dstb + row * DM + cb + bj * 32) = pack8(v);
.LBB0_198:
	v_cvt_pk_bf16_f32 v136, v168, v169
	v_cvt_pk_bf16_f32 v137, v144, v145
	v_cvt_pk_bf16_f32 v138, v166, v167
	v_cvt_pk_bf16_f32 v139, v142, v143
	ds_write_b128 v233, v[136:139]
	ds_read_b128 v[238:241], v234
	ds_read_b128 v[242:245], v234 offset:8192
	v_lshl_add_u64 v[246:247], v[140:141], 0, v[250:251]
	v_lshl_add_u64 v[248:249], v[246:247], 0, s[98:99]
	s_waitcnt lgkmcnt(0)
	global_store_dwordx4 v[246:247], v[238:241], off
	global_store_dwordx4 v[248:249], v[242:245], off
	v_or_b32_e32 v140, 48, v164
	v_ashrrev_i32_e32 v141, 31, v140
	v_lshlrev_b64 v[136:137], 12, v[140:141]
	v_bitop3_b32 v131, v164, s71, 48 bitop3:0xc8
	v_lshl_add_u64 v[136:137], v[132:133], 0, v[136:137]
	v_cmp_le_u32_e64 s[10:11], s76, v131
	s_and_b64 vcc, exec, s[8:9]
	s_mov_b64 s[88:89], -1
	s_cbranch_vccnz .LBB0_205
	s_and_b64 vcc, exec, s[6:7]
	s_cbranch_vccnz .LBB0_202
	s_andn2_b64 vcc, exec, s[86:87]
	s_cbranch_vccnz .LBB0_354
	v_mul_f32_e32 v144, 0xbfb8aa3b, v74
	v_exp_f32_e32 v144, v144
	v_mul_f32_e32 v145, 0xbfb8aa3b, v76
	v_mul_f32_e32 v138, 0xbfb8aa3b, v78
	v_mul_f32_e32 v139, 0xbfb8aa3b, v79
	v_add_f32_e32 v144, 1.0, v144
	v_mul_f32_e32 v142, 0xbfb8aa3b, v80
	v_mul_f32_e32 v143, 0xbfb8aa3b, v81
	v_rcp_f32_e32 v166, v144
	v_mul_f32_e32 v144, 0xbfb8aa3b, v75
	v_exp_f32_e32 v145, v145
	v_mul_f32_e32 v156, 0xbfb8aa3b, v77
	v_exp_f32_e32 v138, v138
	v_exp_f32_e32 v139, v139
	v_exp_f32_e32 v142, v142
	v_exp_f32_e32 v143, v143
	v_exp_f32_e32 v144, v144
	v_exp_f32_e32 v156, v156
	v_add_f32_e32 v145, 1.0, v145
	v_add_f32_e32 v138, 1.0, v138
	v_add_f32_e32 v139, 1.0, v139
	v_add_f32_e32 v142, 1.0, v142
	v_add_f32_e32 v143, 1.0, v143
	v_add_f32_e32 v144, 1.0, v144
	v_rcp_f32_e32 v170, v145
	v_add_f32_e32 v145, 1.0, v156
	v_rcp_f32_e32 v138, v138
	v_rcp_f32_e32 v139, v139
	v_rcp_f32_e32 v142, v142
	v_rcp_f32_e32 v143, v143
	v_rcp_f32_e32 v171, v145
	v_rcp_f32_e32 v167, v144
	v_pk_mul_f32 v[168:169], v[78:79], v[138:139]
	v_pk_mul_f32 v[144:145], v[80:81], v[142:143]
	v_pk_mul_f32 v[142:143], v[76:77], v[170:171]
	v_pk_mul_f32 v[166:167], v[74:75], v[166:167]
	s_cbranch_execz .LBB0_203
	s_branch .LBB0_204

; #define GAS __attribute__((address_space(1)))
;     __device__ __forceinline__ bool operator()(pg8::f32x4 (&acc)[2][2][4][2], const pg8::Unit& u, int wr, int wc, int fr, int fq) const {
;     ...
;                     } else if (g == 4) {
;                         GAS f32x4* o = (GAS f32x4*)(vout + row * DM + cb + bj * 32); o[0] = (f32x4){v[0], v[1], v[2], v[3]}; o[1] = (f32x4){v[4], v[5], v[6], v[7]};
.LBB0_203:
	ds_write_b128 v235, v[78:81]
	ds_write_b128 v235, v[74:77] offset:16
	ds_read_b128 v[238:241], v236
	ds_read_b128 v[242:245], v236 offset:1152
	v_lshl_add_u64 v[246:247], v[136:137], 0, v[252:253]
	v_lshl_add_u64 v[248:249], v[246:247], 0, s[100:101]
	s_waitcnt lgkmcnt(0)
	global_store_dwordx4 v[246:247], v[238:241], off
	global_store_dwordx4 v[248:249], v[242:245], off

; #define GAS __attribute__((address_space(1)))
; __device__ __forceinline__ float sigm(float v) { return __builtin_amdgcn_rcpf(1.f + __builtin_amdgcn_exp2f(-LOG2E * v)); }
; __device__ __forceinline__ v4u pack8(const float* v) { v4u w; w.x = pk2(v[0], v[1]); w.y = pk2(v[2], v[3]); w.z = pk2(v[4], v[5]); w.w = pk2(v[6], v[7]); return w; }
;     __device__ __forceinline__ bool operator()(pg8::f32x4 (&acc)[2][2][4][2], const pg8::Unit& u, int wr, int wc, int fr, int fq) const {
;     ...
;                     if (g == 0) {
;                         const int t = smp ? (rowi & 63) : (rowi & 2047); const int T = smp ? 64 : 2048;
;                         if (t >= T - 3) { const int b = smp ? ((rowi - MP) >> 6) : (rowi >> 11);
;                             GAS f32x4* o = (GAS f32x4*)(out + (smp ? O_CS : O_CP) + (size_t)(b * 3 + (t - (T - 3))) * DM + cb + bj * 32);
;                             o[0] = (f32x4){v[0], v[1], v[2], v[3]}; o[1] = (f32x4){v[4], v[5], v[6], v[7]}; }
;                     } else if (g == 4) {
;                         GAS f32x4* o = (GAS f32x4*)(vout + row * DM + cb + bj * 32); o[0] = (f32x4){v[0], v[1], v[2], v[3]}; o[1] = (f32x4){v[4], v[5], v[6], v[7]};
;                     } else if (g == 1 || g == 5) {
; #pragma unroll
;                         for (int e = 0; e < 8; ++e) v[e] = v[e] * sigm(v[e]);
;                     } else if (g == 6 || g == 7) {
; #pragma unroll
;                         for (int e = 0; e < 8; ++e) v[e] = sigm(v[e]);
;                     }
;                     *(GAS v4u*)(dstb + row * DM + cb + bj * 32) = pack8(v);
.LBB0_209:
	v_lshlrev_b64 v[140:141], 11, v[140:141]
	v_lshl_add_u64 v[140:141], v[134:135], 0, v[140:141]
	v_cvt_pk_bf16_f32 v168, v168, v169
	v_cvt_pk_bf16_f32 v169, v144, v145
	s_and_b64 vcc, exec, s[8:9]
	s_mov_b64 s[88:89], -1
	v_cvt_pk_bf16_f32 v170, v166, v167
	v_cvt_pk_bf16_f32 v171, v142, v143
	ds_write_b128 v232, v[168:171]
	s_cbranch_vccnz .LBB0_216
	s_and_b64 vcc, exec, s[6:7]
	s_cbranch_vccnz .LBB0_213
	s_andn2_b64 vcc, exec, s[86:87]
	s_cbranch_vccnz .LBB0_355
	v_mul_f32_e32 v131, 0xbfb8aa3b, v70
	v_exp_f32_e32 v131, v131
	v_mul_f32_e32 v142, 0xbfb8aa3b, v71
	v_mul_f32_e32 v143, 0xbfb8aa3b, v72
	v_exp_f32_e32 v144, v142
	v_exp_f32_e32 v145, v143
	v_add_f32_e32 v131, 1.0, v131
	v_rcp_f32_e32 v142, v131
	v_add_f32_e32 v131, 1.0, v144
	v_mul_f32_e32 v144, 0xbfb8aa3b, v73
	v_rcp_f32_e32 v143, v131
	v_add_f32_e32 v131, 1.0, v145
	v_exp_f32_e32 v145, v144
	v_mul_f32_e32 v144, 0xbfb8aa3b, v66
	v_exp_f32_e32 v156, v144
	v_rcp_f32_e32 v144, v131
	v_add_f32_e32 v131, 1.0, v145
	v_rcp_f32_e32 v145, v131
	v_add_f32_e32 v131, 1.0, v156
	v_mul_f32_e32 v156, 0xbfb8aa3b, v68
	v_rcp_f32_e32 v166, v131
	v_mul_f32_e32 v131, 0xbfb8aa3b, v67
	v_exp_f32_e32 v156, v156
	v_mul_f32_e32 v165, 0xbfb8aa3b, v69
	v_exp_f32_e32 v131, v131
	v_exp_f32_e32 v165, v165
	v_add_f32_e32 v156, 1.0, v156
	v_rcp_f32_e32 v170, v156
	v_add_f32_e32 v131, 1.0, v131
	v_add_f32_e32 v156, 1.0, v165
	v_rcp_f32_e32 v171, v156
	v_rcp_f32_e32 v167, v131
	v_pk_mul_f32 v[144:145], v[72:73], v[144:145]
	v_pk_mul_f32 v[168:169], v[70:71], v[142:143]
	v_pk_mul_f32 v[142:143], v[68:69], v[170:171]
	v_pk_mul_f32 v[166:167], v[66:67], v[166:167]
	s_cbranch_execz .LBB0_214
	s_branch .LBB0_215

; #define GAS __attribute__((address_space(1)))
;     __device__ __forceinline__ bool operator()(pg8::f32x4 (&acc)[2][2][4][2], const pg8::Unit& u, int wr, int wc, int fr, int fq) const {
;     ...
;                     } else if (g == 4) {
;                         GAS f32x4* o = (GAS f32x4*)(vout + row * DM + cb + bj * 32); o[0] = (f32x4){v[0], v[1], v[2], v[3]}; o[1] = (f32x4){v[4], v[5], v[6], v[7]};
.LBB0_214:
	ds_write_b128 v235, v[70:73]
	ds_write_b128 v235, v[66:69] offset:16
	ds_read_b128 v[238:241], v236
	ds_read_b128 v[242:245], v236 offset:1152
	v_lshl_add_u64 v[246:247], v[136:137], 0, v[252:253]
	v_lshl_add_u64 v[248:249], v[246:247], 0, s[100:101]
	s_waitcnt lgkmcnt(0)
	global_store_dwordx4 v[246:247], v[238:241], off offset:128
	global_store_dwordx4 v[248:249], v[242:245], off offset:128

; #define GAS __attribute__((address_space(1)))
; __device__ __forceinline__ float sigm(float v) { return __builtin_amdgcn_rcpf(1.f + __builtin_amdgcn_exp2f(-LOG2E * v)); }
; __device__ __forceinline__ v4u pack8(const float* v) { v4u w; w.x = pk2(v[0], v[1]); w.y = pk2(v[2], v[3]); w.z = pk2(v[4], v[5]); w.w = pk2(v[6], v[7]); return w; }
;     __device__ __forceinline__ bool operator()(pg8::f32x4 (&acc)[2][2][4][2], const pg8::Unit& u, int wr, int wc, int fr, int fq) const {
;     ...
; #pragma unroll
;         for (int ai = 0; ai < 2; ++ai)
; #pragma unroll
;             for (int m = 0; m < 4; ++m) {
;                 const int rowi = row0 + ai * 128 + m * 16; const size_t row = (size_t)rowi;
; #pragma unroll
;                 for (int bj = 0; bj < 2; ++bj) {
;                     float v[8];
; #pragma unroll
;                     for (int e = 0; e < 8; ++e) v[e] = acc[ai][bj][m][e >> 2][e & 3];
;                     if (g == 0) {
;                         const int t = smp ? (rowi & 63) : (rowi & 2047); const int T = smp ? 64 : 2048;
;                         if (t >= T - 3) { const int b = smp ? ((rowi - MP) >> 6) : (rowi >> 11);
;                             GAS f32x4* o = (GAS f32x4*)(out + (smp ? O_CS : O_CP) + (size_t)(b * 3 + (t - (T - 3))) * DM + cb + bj * 32);
;                             o[0] = (f32x4){v[0], v[1], v[2], v[3]}; o[1] = (f32x4){v[4], v[5], v[6], v[7]}; }
;                     } else if (g == 4) {
;                         GAS f32x4* o = (GAS f32x4*)(vout + row * DM + cb + bj * 32); o[0] = (f32x4){v[0], v[1], v[2], v[3]}; o[1] = (f32x4){v[4], v[5], v[6], v[7]};
;                     } else if (g == 1 || g == 5) {
; #pragma unroll
;                         for (int e = 0; e < 8; ++e) v[e] = v[e] * sigm(v[e]);
;                     } else if (g == 6 || g == 7) {
; #pragma unroll
;                         for (int e = 0; e < 8; ++e) v[e] = sigm(v[e]);
;                     }
;                     *(GAS v4u*)(dstb + row * DM + cb + bj * 32) = pack8(v);
.LBB0_220:
	v_cvt_pk_bf16_f32 v136, v168, v169
	v_cvt_pk_bf16_f32 v137, v144, v145
	v_cvt_pk_bf16_f32 v138, v166, v167
	v_cvt_pk_bf16_f32 v139, v142, v143
	v_add_u32_e32 v142, 0x80, v164
	v_ashrrev_i32_e32 v143, 31, v142
	ds_write_b128 v233, v[136:139]
	ds_read_b128 v[238:241], v234
	ds_read_b128 v[242:245], v234 offset:8192
	v_lshl_add_u64 v[246:247], v[140:141], 0, v[250:251]
	v_lshl_add_u64 v[248:249], v[246:247], 0, s[98:99]
	s_waitcnt lgkmcnt(0)
	global_store_dwordx4 v[246:247], v[238:241], off
	global_store_dwordx4 v[248:249], v[242:245], off
	v_and_b32_e32 v131, s71, v142
	v_cmp_le_u32_e64 s[10:11], s76, v131
	v_lshlrev_b64 v[136:137], 12, v[142:143]
	v_lshl_add_u64 v[138:139], v[132:133], 0, v[136:137]
	s_and_b64 vcc, exec, s[8:9]
	s_mov_b64 s[88:89], -1
	s_cbranch_vccnz .LBB0_227
	s_and_b64 vcc, exec, s[6:7]
	s_cbranch_vccnz .LBB0_224
	s_andn2_b64 vcc, exec, s[86:87]
	s_cbranch_vccnz .LBB0_356
	v_mul_f32_e32 v144, 0xbfb8aa3b, v58
	v_exp_f32_e32 v144, v144
	v_mul_f32_e32 v136, 0xbfb8aa3b, v62
	v_mul_f32_e32 v137, 0xbfb8aa3b, v63
	v_mul_f32_e32 v140, 0xbfb8aa3b, v64
	v_add_f32_e32 v144, 1.0, v144
	v_mul_f32_e32 v141, 0xbfb8aa3b, v65
	v_rcp_f32_e32 v168, v144
	v_mul_f32_e32 v144, 0xbfb8aa3b, v59
	v_mul_f32_e32 v145, 0xbfb8aa3b, v60
	v_mul_f32_e32 v156, 0xbfb8aa3b, v61
	v_exp_f32_e32 v136, v136
	v_exp_f32_e32 v137, v137
	v_exp_f32_e32 v140, v140
	v_exp_f32_e32 v141, v141
	v_exp_f32_e32 v144, v144
	v_exp_f32_e32 v145, v145
	v_exp_f32_e32 v156, v156
	v_add_f32_e32 v136, 1.0, v136
	v_add_f32_e32 v137, 1.0, v137
	v_add_f32_e32 v140, 1.0, v140
	v_add_f32_e32 v141, 1.0, v141
	v_add_f32_e32 v165, 1.0, v144
	v_add_f32_e32 v144, 1.0, v145
	v_add_f32_e32 v145, 1.0, v156
	v_rcp_f32_e32 v136, v136
	v_rcp_f32_e32 v137, v137
	v_rcp_f32_e32 v140, v140
	v_rcp_f32_e32 v141, v141
	v_rcp_f32_e32 v144, v144
	v_rcp_f32_e32 v145, v145
	v_rcp_f32_e32 v169, v165
	v_pk_mul_f32 v[166:167], v[64:65], v[140:141]
	v_pk_mul_f32 v[170:171], v[62:63], v[136:137]
	v_pk_mul_f32 v[144:145], v[60:61], v[144:145]
	v_pk_mul_f32 v[168:169], v[58:59], v[168:169]
	s_cbranch_execz .LBB0_225
	s_branch .LBB0_226

; #define GAS __attribute__((address_space(1)))
;     __device__ __forceinline__ bool operator()(pg8::f32x4 (&acc)[2][2][4][2], const pg8::Unit& u, int wr, int wc, int fr, int fq) const {
;     ...
;                     } else if (g == 4) {
;                         GAS f32x4* o = (GAS f32x4*)(vout + row * DM + cb + bj * 32); o[0] = (f32x4){v[0], v[1], v[2], v[3]}; o[1] = (f32x4){v[4], v[5], v[6], v[7]};
.LBB0_225:
	ds_write_b128 v235, v[62:65]
	ds_write_b128 v235, v[58:61] offset:16
	ds_read_b128 v[238:241], v236
	ds_read_b128 v[242:245], v236 offset:1152
	v_lshl_add_u64 v[246:247], v[138:139], 0, v[252:253]
	v_lshl_add_u64 v[248:249], v[246:247], 0, s[100:101]
	s_waitcnt lgkmcnt(0)
	global_store_dwordx4 v[246:247], v[238:241], off
	global_store_dwordx4 v[248:249], v[242:245], off

; #define GAS __attribute__((address_space(1)))
; __device__ __forceinline__ float sigm(float v) { return __builtin_amdgcn_rcpf(1.f + __builtin_amdgcn_exp2f(-LOG2E * v)); }
; __device__ __forceinline__ v4u pack8(const float* v) { v4u w; w.x = pk2(v[0], v[1]); w.y = pk2(v[2], v[3]); w.z = pk2(v[4], v[5]); w.w = pk2(v[6], v[7]); return w; }
;     __device__ __forceinline__ bool operator()(pg8::f32x4 (&acc)[2][2][4][2], const pg8::Unit& u, int wr, int wc, int fr, int fq) const {
;     ...
;                     if (g == 0) {
;                         const int t = smp ? (rowi & 63) : (rowi & 2047); const int T = smp ? 64 : 2048;
;                         if (t >= T - 3) { const int b = smp ? ((rowi - MP) >> 6) : (rowi >> 11);
;                             GAS f32x4* o = (GAS f32x4*)(out + (smp ? O_CS : O_CP) + (size_t)(b * 3 + (t - (T - 3))) * DM + cb + bj * 32);
;                             o[0] = (f32x4){v[0], v[1], v[2], v[3]}; o[1] = (f32x4){v[4], v[5], v[6], v[7]}; }
;                     } else if (g == 4) {
;                         GAS f32x4* o = (GAS f32x4*)(vout + row * DM + cb + bj * 32); o[0] = (f32x4){v[0], v[1], v[2], v[3]}; o[1] = (f32x4){v[4], v[5], v[6], v[7]};
;                     } else if (g == 1 || g == 5) {
; #pragma unroll
;                         for (int e = 0; e < 8; ++e) v[e] = v[e] * sigm(v[e]);
;                     } else if (g == 6 || g == 7) {
; #pragma unroll
;                         for (int e = 0; e < 8; ++e) v[e] = sigm(v[e]);
;                     }
;                     *(GAS v4u*)(dstb + row * DM + cb + bj * 32) = pack8(v);
.LBB0_231:
	v_lshlrev_b64 v[142:143], 11, v[142:143]
	v_lshl_add_u64 v[142:143], v[134:135], 0, v[142:143]
	s_and_b64 vcc, exec, s[8:9]
	s_mov_b64 s[88:89], -1
	v_cvt_pk_bf16_f32 v174, v170, v171
	v_cvt_pk_bf16_f32 v175, v166, v167
	v_cvt_pk_bf16_f32 v176, v168, v169
	v_cvt_pk_bf16_f32 v177, v144, v145
	ds_write_b128 v232, v[174:177]
	s_cbranch_vccnz .LBB0_238
	s_and_b64 vcc, exec, s[6:7]
	s_cbranch_vccnz .LBB0_235
	s_andn2_b64 vcc, exec, s[86:87]
	s_cbranch_vccnz .LBB0_357
	v_mul_f32_e32 v131, 0xbfb8aa3b, v54
	v_exp_f32_e32 v131, v131
	v_mul_f32_e32 v137, 0xbfb8aa3b, v55
	v_mul_f32_e32 v144, 0xbfb8aa3b, v56
	v_exp_f32_e32 v137, v137
	v_exp_f32_e32 v156, v144
	v_add_f32_e32 v131, 1.0, v131
	v_rcp_f32_e32 v144, v131
	v_add_f32_e32 v131, 1.0, v137
	v_mul_f32_e32 v137, 0xbfb8aa3b, v57
	v_rcp_f32_e32 v145, v131
	v_add_f32_e32 v131, 1.0, v156
	v_exp_f32_e32 v137, v137
	v_mul_f32_e32 v156, 0xbfb8aa3b, v50
	v_exp_f32_e32 v156, v156
	v_rcp_f32_e32 v166, v131
	v_add_f32_e32 v131, 1.0, v137
	v_rcp_f32_e32 v167, v131
	v_add_f32_e32 v131, 1.0, v156
	v_mul_f32_e32 v137, 0xbfb8aa3b, v52
	v_rcp_f32_e32 v168, v131
	v_mul_f32_e32 v131, 0xbfb8aa3b, v51
	v_exp_f32_e32 v137, v137
	v_mul_f32_e32 v156, 0xbfb8aa3b, v53
	v_exp_f32_e32 v131, v131
	v_exp_f32_e32 v156, v156
	v_add_f32_e32 v137, 1.0, v137
	v_rcp_f32_e32 v174, v137
	v_add_f32_e32 v131, 1.0, v131
	v_add_f32_e32 v137, 1.0, v156
	v_rcp_f32_e32 v175, v137
	v_rcp_f32_e32 v169, v131
	v_pk_mul_f32 v[166:167], v[56:57], v[166:167]
	v_pk_mul_f32 v[170:171], v[54:55], v[144:145]
	v_pk_mul_f32 v[144:145], v[52:53], v[174:175]
	v_pk_mul_f32 v[168:169], v[50:51], v[168:169]
	s_cbranch_execz .LBB0_236
	s_branch .LBB0_237

; #define GAS __attribute__((address_space(1)))
;     __device__ __forceinline__ bool operator()(pg8::f32x4 (&acc)[2][2][4][2], const pg8::Unit& u, int wr, int wc, int fr, int fq) const {
;     ...
;                     } else if (g == 4) {
;                         GAS f32x4* o = (GAS f32x4*)(vout + row * DM + cb + bj * 32); o[0] = (f32x4){v[0], v[1], v[2], v[3]}; o[1] = (f32x4){v[4], v[5], v[6], v[7]};
.LBB0_236:
	ds_write_b128 v235, v[54:57]
	ds_write_b128 v235, v[50:53] offset:16
	ds_read_b128 v[238:241], v236
	ds_read_b128 v[242:245], v236 offset:1152
	v_lshl_add_u64 v[246:247], v[138:139], 0, v[252:253]
	v_lshl_add_u64 v[248:249], v[246:247], 0, s[100:101]
	s_waitcnt lgkmcnt(0)
	global_store_dwordx4 v[246:247], v[238:241], off offset:128
	global_store_dwordx4 v[248:249], v[242:245], off offset:128

; #define GAS __attribute__((address_space(1)))
; __device__ __forceinline__ float sigm(float v) { return __builtin_amdgcn_rcpf(1.f + __builtin_amdgcn_exp2f(-LOG2E * v)); }
; __device__ __forceinline__ v4u pack8(const float* v) { v4u w; w.x = pk2(v[0], v[1]); w.y = pk2(v[2], v[3]); w.z = pk2(v[4], v[5]); w.w = pk2(v[6], v[7]); return w; }
;     __device__ __forceinline__ bool operator()(pg8::f32x4 (&acc)[2][2][4][2], const pg8::Unit& u, int wr, int wc, int fr, int fq) const {
;     ...
; #pragma unroll
;         for (int ai = 0; ai < 2; ++ai)
; #pragma unroll
;             for (int m = 0; m < 4; ++m) {
;                 const int rowi = row0 + ai * 128 + m * 16; const size_t row = (size_t)rowi;
; #pragma unroll
;                 for (int bj = 0; bj < 2; ++bj) {
;                     float v[8];
; #pragma unroll
;                     for (int e = 0; e < 8; ++e) v[e] = acc[ai][bj][m][e >> 2][e & 3];
;                     if (g == 0) {
;                         const int t = smp ? (rowi & 63) : (rowi & 2047); const int T = smp ? 64 : 2048;
;                         if (t >= T - 3) { const int b = smp ? ((rowi - MP) >> 6) : (rowi >> 11);
;                             GAS f32x4* o = (GAS f32x4*)(out + (smp ? O_CS : O_CP) + (size_t)(b * 3 + (t - (T - 3))) * DM + cb + bj * 32);
;                             o[0] = (f32x4){v[0], v[1], v[2], v[3]}; o[1] = (f32x4){v[4], v[5], v[6], v[7]}; }
;                     } else if (g == 4) {
;                         GAS f32x4* o = (GAS f32x4*)(vout + row * DM + cb + bj * 32); o[0] = (f32x4){v[0], v[1], v[2], v[3]}; o[1] = (f32x4){v[4], v[5], v[6], v[7]};
;                     } else if (g == 1 || g == 5) {
; #pragma unroll
;                         for (int e = 0; e < 8; ++e) v[e] = v[e] * sigm(v[e]);
;                     } else if (g == 6 || g == 7) {
; #pragma unroll
;                         for (int e = 0; e < 8; ++e) v[e] = sigm(v[e]);
;                     }
;                     *(GAS v4u*)(dstb + row * DM + cb + bj * 32) = pack8(v);
.LBB0_242:
	v_cvt_pk_bf16_f32 v138, v170, v171
	v_cvt_pk_bf16_f32 v139, v166, v167
	v_cvt_pk_bf16_f32 v140, v168, v169
	v_cvt_pk_bf16_f32 v141, v144, v145
	ds_write_b128 v233, v[138:141]
	ds_read_b128 v[238:241], v234
	ds_read_b128 v[242:245], v234 offset:8192
	v_lshl_add_u64 v[246:247], v[142:143], 0, v[250:251]
	v_lshl_add_u64 v[248:249], v[246:247], 0, s[98:99]
	s_waitcnt lgkmcnt(0)
	global_store_dwordx4 v[246:247], v[238:241], off
	global_store_dwordx4 v[248:249], v[242:245], off
	v_add_u32_e32 v142, 0x90, v164
	v_ashrrev_i32_e32 v143, 31, v142
	v_lshlrev_b64 v[138:139], 12, v[142:143]
	v_and_b32_e32 v131, s71, v142
	v_lshl_add_u64 v[138:139], v[132:133], 0, v[138:139]
	v_cmp_le_u32_e64 s[10:11], s76, v131
	s_and_b64 vcc, exec, s[8:9]
	s_mov_b64 s[88:89], -1
	s_cbranch_vccnz .LBB0_249
	s_and_b64 vcc, exec, s[6:7]
	s_cbranch_vccnz .LBB0_246
	s_andn2_b64 vcc, exec, s[86:87]
	s_cbranch_vccnz .LBB0_358
	v_mul_f32_e32 v137, 0xbfb8aa3b, v46
	v_exp_f32_e32 v137, v137
	v_mul_f32_e32 v140, 0xbfb8aa3b, v47
	v_mul_f32_e32 v141, 0xbfb8aa3b, v48
	v_exp_f32_e32 v144, v140
	v_exp_f32_e32 v145, v141
	v_add_f32_e32 v137, 1.0, v137
	v_rcp_f32_e32 v140, v137
	v_add_f32_e32 v137, 1.0, v144
	v_mul_f32_e32 v144, 0xbfb8aa3b, v49
	v_rcp_f32_e32 v141, v137
	v_add_f32_e32 v137, 1.0, v145
	v_exp_f32_e32 v145, v144
	v_mul_f32_e32 v144, 0xbfb8aa3b, v42
	v_exp_f32_e32 v156, v144
	v_rcp_f32_e32 v144, v137
	v_add_f32_e32 v137, 1.0, v145
	v_rcp_f32_e32 v145, v137
	v_add_f32_e32 v137, 1.0, v156
	v_mul_f32_e32 v156, 0xbfb8aa3b, v44
	v_rcp_f32_e32 v168, v137
	v_mul_f32_e32 v137, 0xbfb8aa3b, v43
	v_exp_f32_e32 v156, v156
	v_mul_f32_e32 v165, 0xbfb8aa3b, v45
	v_exp_f32_e32 v137, v137
	v_exp_f32_e32 v165, v165
	v_add_f32_e32 v156, 1.0, v156
	v_rcp_f32_e32 v174, v156
	v_add_f32_e32 v137, 1.0, v137
	v_add_f32_e32 v156, 1.0, v165
	v_rcp_f32_e32 v175, v156
	v_rcp_f32_e32 v169, v137
	v_pk_mul_f32 v[166:167], v[48:49], v[144:145]
	v_pk_mul_f32 v[170:171], v[46:47], v[140:141]
	v_pk_mul_f32 v[144:145], v[44:45], v[174:175]
	v_pk_mul_f32 v[168:169], v[42:43], v[168:169]
	s_cbranch_execz .LBB0_247
	s_branch .LBB0_248

; #define GAS __attribute__((address_space(1)))
;     __device__ __forceinline__ bool operator()(pg8::f32x4 (&acc)[2][2][4][2], const pg8::Unit& u, int wr, int wc, int fr, int fq) const {
;     ...
;                     } else if (g == 4) {
;                         GAS f32x4* o = (GAS f32x4*)(vout + row * DM + cb + bj * 32); o[0] = (f32x4){v[0], v[1], v[2], v[3]}; o[1] = (f32x4){v[4], v[5], v[6], v[7]};
.LBB0_247:
	ds_write_b128 v235, v[46:49]
	ds_write_b128 v235, v[42:45] offset:16
	ds_read_b128 v[238:241], v236
	ds_read_b128 v[242:245], v236 offset:1152
	v_lshl_add_u64 v[246:247], v[138:139], 0, v[252:253]
	v_lshl_add_u64 v[248:249], v[246:247], 0, s[100:101]
	s_waitcnt lgkmcnt(0)
	global_store_dwordx4 v[246:247], v[238:241], off
	global_store_dwordx4 v[248:249], v[242:245], off

; #define GAS __attribute__((address_space(1)))
; __device__ __forceinline__ float sigm(float v) { return __builtin_amdgcn_rcpf(1.f + __builtin_amdgcn_exp2f(-LOG2E * v)); }
; __device__ __forceinline__ v4u pack8(const float* v) { v4u w; w.x = pk2(v[0], v[1]); w.y = pk2(v[2], v[3]); w.z = pk2(v[4], v[5]); w.w = pk2(v[6], v[7]); return w; }
;     __device__ __forceinline__ bool operator()(pg8::f32x4 (&acc)[2][2][4][2], const pg8::Unit& u, int wr, int wc, int fr, int fq) const {
;     ...
;                     if (g == 0) {
;                         const int t = smp ? (rowi & 63) : (rowi & 2047); const int T = smp ? 64 : 2048;
;                         if (t >= T - 3) { const int b = smp ? ((rowi - MP) >> 6) : (rowi >> 11);
;                             GAS f32x4* o = (GAS f32x4*)(out + (smp ? O_CS : O_CP) + (size_t)(b * 3 + (t - (T - 3))) * DM + cb + bj * 32);
;                             o[0] = (f32x4){v[0], v[1], v[2], v[3]}; o[1] = (f32x4){v[4], v[5], v[6], v[7]}; }
;                     } else if (g == 4) {
;                         GAS f32x4* o = (GAS f32x4*)(vout + row * DM + cb + bj * 32); o[0] = (f32x4){v[0], v[1], v[2], v[3]}; o[1] = (f32x4){v[4], v[5], v[6], v[7]};
;                     } else if (g == 1 || g == 5) {
; #pragma unroll
;                         for (int e = 0; e < 8; ++e) v[e] = v[e] * sigm(v[e]);
;                     } else if (g == 6 || g == 7) {
; #pragma unroll
;                         for (int e = 0; e < 8; ++e) v[e] = sigm(v[e]);
;                     }
;                     *(GAS v4u*)(dstb + row * DM + cb + bj * 32) = pack8(v);
.LBB0_253:
	v_lshlrev_b64 v[142:143], 11, v[142:143]
	v_lshl_add_u64 v[142:143], v[134:135], 0, v[142:143]
	s_and_b64 vcc, exec, s[8:9]
	s_mov_b64 s[88:89], -1
	v_cvt_pk_bf16_f32 v174, v170, v171
	v_cvt_pk_bf16_f32 v175, v166, v167
	v_cvt_pk_bf16_f32 v176, v168, v169
	v_cvt_pk_bf16_f32 v177, v144, v145
	ds_write_b128 v232, v[174:177]
	s_cbranch_vccnz .LBB0_260
	s_and_b64 vcc, exec, s[6:7]
	s_cbranch_vccnz .LBB0_257
	s_andn2_b64 vcc, exec, s[86:87]
	s_cbranch_vccnz .LBB0_359
	v_mul_f32_e32 v131, 0xbfb8aa3b, v38
	v_exp_f32_e32 v131, v131
	v_mul_f32_e32 v137, 0xbfb8aa3b, v39
	v_mul_f32_e32 v144, 0xbfb8aa3b, v40
	v_exp_f32_e32 v137, v137
	v_exp_f32_e32 v156, v144
	v_add_f32_e32 v131, 1.0, v131
	v_rcp_f32_e32 v144, v131
	v_add_f32_e32 v131, 1.0, v137
	v_mul_f32_e32 v137, 0xbfb8aa3b, v41
	v_rcp_f32_e32 v145, v131
	v_add_f32_e32 v131, 1.0, v156
	v_exp_f32_e32 v137, v137
	v_mul_f32_e32 v156, 0xbfb8aa3b, v34
	v_exp_f32_e32 v156, v156
	v_rcp_f32_e32 v166, v131
	v_add_f32_e32 v131, 1.0, v137
	v_rcp_f32_e32 v167, v131
	v_add_f32_e32 v131, 1.0, v156
	v_mul_f32_e32 v137, 0xbfb8aa3b, v36
	v_rcp_f32_e32 v168, v131
	v_mul_f32_e32 v131, 0xbfb8aa3b, v35
	v_exp_f32_e32 v137, v137
	v_mul_f32_e32 v156, 0xbfb8aa3b, v37
	v_exp_f32_e32 v131, v131
	v_exp_f32_e32 v156, v156
	v_add_f32_e32 v137, 1.0, v137
	v_rcp_f32_e32 v174, v137
	v_add_f32_e32 v131, 1.0, v131
	v_add_f32_e32 v137, 1.0, v156
	v_rcp_f32_e32 v175, v137
	v_rcp_f32_e32 v169, v131
	v_pk_mul_f32 v[166:167], v[40:41], v[166:167]
	v_pk_mul_f32 v[170:171], v[38:39], v[144:145]
	v_pk_mul_f32 v[144:145], v[36:37], v[174:175]
	v_pk_mul_f32 v[168:169], v[34:35], v[168:169]
	s_cbranch_execz .LBB0_258
	s_branch .LBB0_259

; #define GAS __attribute__((address_space(1)))
;     __device__ __forceinline__ bool operator()(pg8::f32x4 (&acc)[2][2][4][2], const pg8::Unit& u, int wr, int wc, int fr, int fq) const {
;     ...
;                     } else if (g == 4) {
;                         GAS f32x4* o = (GAS f32x4*)(vout + row * DM + cb + bj * 32); o[0] = (f32x4){v[0], v[1], v[2], v[3]}; o[1] = (f32x4){v[4], v[5], v[6], v[7]};
.LBB0_258:
	ds_write_b128 v235, v[38:41]
	ds_write_b128 v235, v[34:37] offset:16
	ds_read_b128 v[238:241], v236
	ds_read_b128 v[242:245], v236 offset:1152
	v_lshl_add_u64 v[246:247], v[138:139], 0, v[252:253]
	v_lshl_add_u64 v[248:249], v[246:247], 0, s[100:101]
	s_waitcnt lgkmcnt(0)
	global_store_dwordx4 v[246:247], v[238:241], off offset:128
	global_store_dwordx4 v[248:249], v[242:245], off offset:128

; #define GAS __attribute__((address_space(1)))
; __device__ __forceinline__ float sigm(float v) { return __builtin_amdgcn_rcpf(1.f + __builtin_amdgcn_exp2f(-LOG2E * v)); }
; __device__ __forceinline__ v4u pack8(const float* v) { v4u w; w.x = pk2(v[0], v[1]); w.y = pk2(v[2], v[3]); w.z = pk2(v[4], v[5]); w.w = pk2(v[6], v[7]); return w; }
;     __device__ __forceinline__ bool operator()(pg8::f32x4 (&acc)[2][2][4][2], const pg8::Unit& u, int wr, int wc, int fr, int fq) const {
;     ...
; #pragma unroll
;         for (int ai = 0; ai < 2; ++ai)
; #pragma unroll
;             for (int m = 0; m < 4; ++m) {
;                 const int rowi = row0 + ai * 128 + m * 16; const size_t row = (size_t)rowi;
; #pragma unroll
;                 for (int bj = 0; bj < 2; ++bj) {
;                     float v[8];
; #pragma unroll
;                     for (int e = 0; e < 8; ++e) v[e] = acc[ai][bj][m][e >> 2][e & 3];
;                     if (g == 0) {
;                         const int t = smp ? (rowi & 63) : (rowi & 2047); const int T = smp ? 64 : 2048;
;                         if (t >= T - 3) { const int b = smp ? ((rowi - MP) >> 6) : (rowi >> 11);
;                             GAS f32x4* o = (GAS f32x4*)(out + (smp ? O_CS : O_CP) + (size_t)(b * 3 + (t - (T - 3))) * DM + cb + bj * 32);
;                             o[0] = (f32x4){v[0], v[1], v[2], v[3]}; o[1] = (f32x4){v[4], v[5], v[6], v[7]}; }
;                     } else if (g == 4) {
;                         GAS f32x4* o = (GAS f32x4*)(vout + row * DM + cb + bj * 32); o[0] = (f32x4){v[0], v[1], v[2], v[3]}; o[1] = (f32x4){v[4], v[5], v[6], v[7]};
;                     } else if (g == 1 || g == 5) {
; #pragma unroll
;                         for (int e = 0; e < 8; ++e) v[e] = v[e] * sigm(v[e]);
;                     } else if (g == 6 || g == 7) {
; #pragma unroll
;                         for (int e = 0; e < 8; ++e) v[e] = sigm(v[e]);
;                     }
;                     *(GAS v4u*)(dstb + row * DM + cb + bj * 32) = pack8(v);
.LBB0_264:
	v_cvt_pk_bf16_f32 v138, v170, v171
	v_cvt_pk_bf16_f32 v139, v166, v167
	v_cvt_pk_bf16_f32 v140, v168, v169
	v_cvt_pk_bf16_f32 v141, v144, v145
	ds_write_b128 v233, v[138:141]
	ds_read_b128 v[238:241], v234
	ds_read_b128 v[242:245], v234 offset:8192
	v_lshl_add_u64 v[246:247], v[142:143], 0, v[250:251]
	v_lshl_add_u64 v[248:249], v[246:247], 0, s[98:99]
	s_waitcnt lgkmcnt(0)
	global_store_dwordx4 v[246:247], v[238:241], off
	global_store_dwordx4 v[248:249], v[242:245], off
	v_add_u32_e32 v142, 0xa0, v164
	v_ashrrev_i32_e32 v143, 31, v142
	v_lshlrev_b64 v[138:139], 12, v[142:143]
	v_and_b32_e32 v131, s71, v142
	v_lshl_add_u64 v[138:139], v[132:133], 0, v[138:139]
	v_cmp_le_u32_e64 s[10:11], s76, v131
	s_and_b64 vcc, exec, s[8:9]
	s_mov_b64 s[88:89], -1
	s_cbranch_vccnz .LBB0_271
	s_and_b64 vcc, exec, s[6:7]
	s_cbranch_vccnz .LBB0_268
	s_andn2_b64 vcc, exec, s[86:87]
	s_cbranch_vccnz .LBB0_360
	v_mul_f32_e32 v137, 0xbfb8aa3b, v30
	v_exp_f32_e32 v137, v137
	v_mul_f32_e32 v140, 0xbfb8aa3b, v31
	v_mul_f32_e32 v141, 0xbfb8aa3b, v32
	v_exp_f32_e32 v144, v140
	v_exp_f32_e32 v145, v141
	v_add_f32_e32 v137, 1.0, v137
	v_rcp_f32_e32 v140, v137
	v_add_f32_e32 v137, 1.0, v144
	v_mul_f32_e32 v144, 0xbfb8aa3b, v33
	v_rcp_f32_e32 v141, v137
	v_add_f32_e32 v137, 1.0, v145
	v_exp_f32_e32 v145, v144
	v_mul_f32_e32 v144, 0xbfb8aa3b, v26
	v_exp_f32_e32 v156, v144
	v_rcp_f32_e32 v144, v137
	v_add_f32_e32 v137, 1.0, v145
	v_rcp_f32_e32 v145, v137
	v_add_f32_e32 v137, 1.0, v156
	v_mul_f32_e32 v156, 0xbfb8aa3b, v28
	v_rcp_f32_e32 v168, v137
	v_mul_f32_e32 v137, 0xbfb8aa3b, v27
	v_exp_f32_e32 v156, v156
	v_mul_f32_e32 v165, 0xbfb8aa3b, v29
	v_exp_f32_e32 v137, v137
	v_exp_f32_e32 v165, v165
	v_add_f32_e32 v156, 1.0, v156
	v_rcp_f32_e32 v174, v156
	v_add_f32_e32 v137, 1.0, v137
	v_add_f32_e32 v156, 1.0, v165
	v_rcp_f32_e32 v175, v156
	v_rcp_f32_e32 v169, v137
	v_pk_mul_f32 v[166:167], v[32:33], v[144:145]
	v_pk_mul_f32 v[170:171], v[30:31], v[140:141]
	v_pk_mul_f32 v[144:145], v[28:29], v[174:175]
	v_pk_mul_f32 v[168:169], v[26:27], v[168:169]
	s_cbranch_execz .LBB0_269
	s_branch .LBB0_270

; #define GAS __attribute__((address_space(1)))
;     __device__ __forceinline__ bool operator()(pg8::f32x4 (&acc)[2][2][4][2], const pg8::Unit& u, int wr, int wc, int fr, int fq) const {
;     ...
;                     } else if (g == 4) {
;                         GAS f32x4* o = (GAS f32x4*)(vout + row * DM + cb + bj * 32); o[0] = (f32x4){v[0], v[1], v[2], v[3]}; o[1] = (f32x4){v[4], v[5], v[6], v[7]};
.LBB0_269:
	ds_write_b128 v235, v[30:33]
	ds_write_b128 v235, v[26:29] offset:16
	ds_read_b128 v[238:241], v236
	ds_read_b128 v[242:245], v236 offset:1152
	v_lshl_add_u64 v[246:247], v[138:139], 0, v[252:253]
	v_lshl_add_u64 v[248:249], v[246:247], 0, s[100:101]
	s_waitcnt lgkmcnt(0)
	global_store_dwordx4 v[246:247], v[238:241], off
	global_store_dwordx4 v[248:249], v[242:245], off

; #define GAS __attribute__((address_space(1)))
; __device__ __forceinline__ float sigm(float v) { return __builtin_amdgcn_rcpf(1.f + __builtin_amdgcn_exp2f(-LOG2E * v)); }
; __device__ __forceinline__ v4u pack8(const float* v) { v4u w; w.x = pk2(v[0], v[1]); w.y = pk2(v[2], v[3]); w.z = pk2(v[4], v[5]); w.w = pk2(v[6], v[7]); return w; }
;     __device__ __forceinline__ bool operator()(pg8::f32x4 (&acc)[2][2][4][2], const pg8::Unit& u, int wr, int wc, int fr, int fq) const {
;     ...
;                     if (g == 0) {
;                         const int t = smp ? (rowi & 63) : (rowi & 2047); const int T = smp ? 64 : 2048;
;                         if (t >= T - 3) { const int b = smp ? ((rowi - MP) >> 6) : (rowi >> 11);
;                             GAS f32x4* o = (GAS f32x4*)(out + (smp ? O_CS : O_CP) + (size_t)(b * 3 + (t - (T - 3))) * DM + cb + bj * 32);
;                             o[0] = (f32x4){v[0], v[1], v[2], v[3]}; o[1] = (f32x4){v[4], v[5], v[6], v[7]}; }
;                     } else if (g == 4) {
;                         GAS f32x4* o = (GAS f32x4*)(vout + row * DM + cb + bj * 32); o[0] = (f32x4){v[0], v[1], v[2], v[3]}; o[1] = (f32x4){v[4], v[5], v[6], v[7]};
;                     } else if (g == 1 || g == 5) {
; #pragma unroll
;                         for (int e = 0; e < 8; ++e) v[e] = v[e] * sigm(v[e]);
;                     } else if (g == 6 || g == 7) {
; #pragma unroll
;                         for (int e = 0; e < 8; ++e) v[e] = sigm(v[e]);
;                     }
;                     *(GAS v4u*)(dstb + row * DM + cb + bj * 32) = pack8(v);
.LBB0_275:
	v_lshlrev_b64 v[142:143], 11, v[142:143]
	v_lshl_add_u64 v[142:143], v[134:135], 0, v[142:143]
	s_and_b64 vcc, exec, s[8:9]
	s_mov_b64 s[88:89], -1
	v_cvt_pk_bf16_f32 v174, v170, v171
	v_cvt_pk_bf16_f32 v175, v166, v167
	v_cvt_pk_bf16_f32 v176, v168, v169
	v_cvt_pk_bf16_f32 v177, v144, v145
	ds_write_b128 v232, v[174:177]
	s_cbranch_vccnz .LBB0_282
	s_and_b64 vcc, exec, s[6:7]
	s_cbranch_vccnz .LBB0_279
	s_andn2_b64 vcc, exec, s[86:87]
	s_cbranch_vccnz .LBB0_361
	v_mul_f32_e32 v131, 0xbfb8aa3b, v22
	v_exp_f32_e32 v131, v131
	v_mul_f32_e32 v137, 0xbfb8aa3b, v23
	v_mul_f32_e32 v144, 0xbfb8aa3b, v24
	v_exp_f32_e32 v137, v137
	v_exp_f32_e32 v156, v144
	v_add_f32_e32 v131, 1.0, v131
	v_rcp_f32_e32 v144, v131
	v_add_f32_e32 v131, 1.0, v137
	v_mul_f32_e32 v137, 0xbfb8aa3b, v25
	v_rcp_f32_e32 v145, v131
	v_add_f32_e32 v131, 1.0, v156
	v_exp_f32_e32 v137, v137
	v_mul_f32_e32 v156, 0xbfb8aa3b, v18
	v_exp_f32_e32 v156, v156
	v_rcp_f32_e32 v166, v131
	v_add_f32_e32 v131, 1.0, v137
	v_rcp_f32_e32 v167, v131
	v_add_f32_e32 v131, 1.0, v156
	v_mul_f32_e32 v137, 0xbfb8aa3b, v20
	v_rcp_f32_e32 v168, v131
	v_mul_f32_e32 v131, 0xbfb8aa3b, v19
	v_exp_f32_e32 v137, v137
	v_mul_f32_e32 v156, 0xbfb8aa3b, v21
	v_exp_f32_e32 v131, v131
	v_exp_f32_e32 v156, v156
	v_add_f32_e32 v137, 1.0, v137
	v_rcp_f32_e32 v174, v137
	v_add_f32_e32 v131, 1.0, v131
	v_add_f32_e32 v137, 1.0, v156
	v_rcp_f32_e32 v175, v137
	v_rcp_f32_e32 v169, v131
	v_pk_mul_f32 v[166:167], v[24:25], v[166:167]
	v_pk_mul_f32 v[170:171], v[22:23], v[144:145]
	v_pk_mul_f32 v[144:145], v[20:21], v[174:175]
	v_pk_mul_f32 v[168:169], v[18:19], v[168:169]
	s_cbranch_execz .LBB0_280
	s_branch .LBB0_281

; #define GAS __attribute__((address_space(1)))
;     __device__ __forceinline__ bool operator()(pg8::f32x4 (&acc)[2][2][4][2], const pg8::Unit& u, int wr, int wc, int fr, int fq) const {
;     ...
;                     } else if (g == 4) {
;                         GAS f32x4* o = (GAS f32x4*)(vout + row * DM + cb + bj * 32); o[0] = (f32x4){v[0], v[1], v[2], v[3]}; o[1] = (f32x4){v[4], v[5], v[6], v[7]};
.LBB0_280:
	ds_write_b128 v235, v[22:25]
	ds_write_b128 v235, v[18:21] offset:16
	ds_read_b128 v[238:241], v236
	ds_read_b128 v[242:245], v236 offset:1152
	v_lshl_add_u64 v[246:247], v[138:139], 0, v[252:253]
	v_lshl_add_u64 v[248:249], v[246:247], 0, s[100:101]
	s_waitcnt lgkmcnt(0)
	global_store_dwordx4 v[246:247], v[238:241], off offset:128
	global_store_dwordx4 v[248:249], v[242:245], off offset:128

; #define GAS __attribute__((address_space(1)))
; __device__ __forceinline__ float sigm(float v) { return __builtin_amdgcn_rcpf(1.f + __builtin_amdgcn_exp2f(-LOG2E * v)); }
; __device__ __forceinline__ v4u pack8(const float* v) { v4u w; w.x = pk2(v[0], v[1]); w.y = pk2(v[2], v[3]); w.z = pk2(v[4], v[5]); w.w = pk2(v[6], v[7]); return w; }
;     __device__ __forceinline__ bool operator()(pg8::f32x4 (&acc)[2][2][4][2], const pg8::Unit& u, int wr, int wc, int fr, int fq) const {
;     ...
; #pragma unroll
;         for (int ai = 0; ai < 2; ++ai)
; #pragma unroll
;             for (int m = 0; m < 4; ++m) {
;                 const int rowi = row0 + ai * 128 + m * 16; const size_t row = (size_t)rowi;
; #pragma unroll
;                 for (int bj = 0; bj < 2; ++bj) {
;                     float v[8];
; #pragma unroll
;                     for (int e = 0; e < 8; ++e) v[e] = acc[ai][bj][m][e >> 2][e & 3];
;                     if (g == 0) {
;                         const int t = smp ? (rowi & 63) : (rowi & 2047); const int T = smp ? 64 : 2048;
;                         if (t >= T - 3) { const int b = smp ? ((rowi - MP) >> 6) : (rowi >> 11);
;                             GAS f32x4* o = (GAS f32x4*)(out + (smp ? O_CS : O_CP) + (size_t)(b * 3 + (t - (T - 3))) * DM + cb + bj * 32);
;                             o[0] = (f32x4){v[0], v[1], v[2], v[3]}; o[1] = (f32x4){v[4], v[5], v[6], v[7]}; }
;                     } else if (g == 4) {
;                         GAS f32x4* o = (GAS f32x4*)(vout + row * DM + cb + bj * 32); o[0] = (f32x4){v[0], v[1], v[2], v[3]}; o[1] = (f32x4){v[4], v[5], v[6], v[7]};
;                     } else if (g == 1 || g == 5) {
; #pragma unroll
;                         for (int e = 0; e < 8; ++e) v[e] = v[e] * sigm(v[e]);
;                     } else if (g == 6 || g == 7) {
; #pragma unroll
;                         for (int e = 0; e < 8; ++e) v[e] = sigm(v[e]);
;                     }
;                     *(GAS v4u*)(dstb + row * DM + cb + bj * 32) = pack8(v);
.LBB0_286:
	v_cvt_pk_bf16_f32 v138, v170, v171
	v_cvt_pk_bf16_f32 v139, v166, v167
	v_cvt_pk_bf16_f32 v140, v168, v169
	v_cvt_pk_bf16_f32 v141, v144, v145
	ds_write_b128 v233, v[138:141]
	ds_read_b128 v[238:241], v234
	ds_read_b128 v[242:245], v234 offset:8192
	v_lshl_add_u64 v[246:247], v[142:143], 0, v[250:251]
	v_lshl_add_u64 v[248:249], v[246:247], 0, s[98:99]
	s_waitcnt lgkmcnt(0)
	global_store_dwordx4 v[246:247], v[238:241], off
	global_store_dwordx4 v[248:249], v[242:245], off
	s_and_b64 vcc, exec, s[8:9]
	s_mov_b64 s[88:89], -1
	v_add_u32_e32 v138, 0xb0, v164
	v_ashrrev_i32_e32 v139, 31, v138
	v_lshlrev_b64 v[140:141], 12, v[138:139]
	v_and_b32_e32 v131, s71, v138
	v_lshl_add_u64 v[132:133], v[132:133], 0, v[140:141]
	v_cmp_le_u32_e64 s[10:11], s76, v131
	s_cbranch_vccnz .LBB0_293
	s_and_b64 vcc, exec, s[6:7]
	s_cbranch_vccnz .LBB0_290
	s_andn2_b64 vcc, exec, s[86:87]
	s_cbranch_vccnz .LBB0_362
	v_mul_f32_e32 v137, 0xbfb8aa3b, v14
	v_exp_f32_e32 v137, v137
	v_mul_f32_e32 v140, 0xbfb8aa3b, v15
	v_mul_f32_e32 v141, 0xbfb8aa3b, v16
	v_exp_f32_e32 v142, v140
	v_exp_f32_e32 v143, v141
	v_add_f32_e32 v137, 1.0, v137
	v_rcp_f32_e32 v140, v137
	v_add_f32_e32 v137, 1.0, v142
	v_mul_f32_e32 v142, 0xbfb8aa3b, v17
	v_rcp_f32_e32 v141, v137
	v_add_f32_e32 v137, 1.0, v143
	v_exp_f32_e32 v143, v142
	v_mul_f32_e32 v142, 0xbfb8aa3b, v10
	v_exp_f32_e32 v144, v142
	v_rcp_f32_e32 v142, v137
	v_add_f32_e32 v137, 1.0, v143
	v_rcp_f32_e32 v143, v137
	v_add_f32_e32 v137, 1.0, v144
	v_mul_f32_e32 v145, 0xbfb8aa3b, v12
	v_rcp_f32_e32 v144, v137
	v_mul_f32_e32 v137, 0xbfb8aa3b, v11
	v_exp_f32_e32 v145, v145
	v_mul_f32_e32 v156, 0xbfb8aa3b, v13
	v_exp_f32_e32 v137, v137
	v_exp_f32_e32 v156, v156
	v_add_f32_e32 v145, 1.0, v145
	v_rcp_f32_e32 v168, v145
	v_add_f32_e32 v137, 1.0, v137
	v_add_f32_e32 v145, 1.0, v156
	v_rcp_f32_e32 v169, v145
	v_rcp_f32_e32 v145, v137
	v_pk_mul_f32 v[142:143], v[16:17], v[142:143]
	v_pk_mul_f32 v[166:167], v[14:15], v[140:141]
	v_pk_mul_f32 v[140:141], v[12:13], v[168:169]
	v_pk_mul_f32 v[144:145], v[10:11], v[144:145]
	s_cbranch_execz .LBB0_291
	s_branch .LBB0_292

; #define GAS __attribute__((address_space(1)))
;     __device__ __forceinline__ bool operator()(pg8::f32x4 (&acc)[2][2][4][2], const pg8::Unit& u, int wr, int wc, int fr, int fq) const {
;     ...
;                     } else if (g == 4) {
;                         GAS f32x4* o = (GAS f32x4*)(vout + row * DM + cb + bj * 32); o[0] = (f32x4){v[0], v[1], v[2], v[3]}; o[1] = (f32x4){v[4], v[5], v[6], v[7]};
.LBB0_291:
	ds_write_b128 v235, v[14:17]
	ds_write_b128 v235, v[10:13] offset:16
	ds_read_b128 v[238:241], v236
	ds_read_b128 v[242:245], v236 offset:1152
	v_lshl_add_u64 v[246:247], v[132:133], 0, v[252:253]
	v_lshl_add_u64 v[248:249], v[246:247], 0, s[100:101]
	s_waitcnt lgkmcnt(0)
	global_store_dwordx4 v[246:247], v[238:241], off
	global_store_dwordx4 v[248:249], v[242:245], off

; #define GAS __attribute__((address_space(1)))
; __device__ __forceinline__ float sigm(float v) { return __builtin_amdgcn_rcpf(1.f + __builtin_amdgcn_exp2f(-LOG2E * v)); }
; __device__ __forceinline__ v4u pack8(const float* v) { v4u w; w.x = pk2(v[0], v[1]); w.y = pk2(v[2], v[3]); w.z = pk2(v[4], v[5]); w.w = pk2(v[6], v[7]); return w; }
;     __device__ __forceinline__ bool operator()(pg8::f32x4 (&acc)[2][2][4][2], const pg8::Unit& u, int wr, int wc, int fr, int fq) const {
;     ...
;                     if (g == 0) {
;                         const int t = smp ? (rowi & 63) : (rowi & 2047); const int T = smp ? 64 : 2048;
;                         if (t >= T - 3) { const int b = smp ? ((rowi - MP) >> 6) : (rowi >> 11);
;                             GAS f32x4* o = (GAS f32x4*)(out + (smp ? O_CS : O_CP) + (size_t)(b * 3 + (t - (T - 3))) * DM + cb + bj * 32);
;                             o[0] = (f32x4){v[0], v[1], v[2], v[3]}; o[1] = (f32x4){v[4], v[5], v[6], v[7]}; }
;                     } else if (g == 4) {
;                         GAS f32x4* o = (GAS f32x4*)(vout + row * DM + cb + bj * 32); o[0] = (f32x4){v[0], v[1], v[2], v[3]}; o[1] = (f32x4){v[4], v[5], v[6], v[7]};
;                     } else if (g == 1 || g == 5) {
; #pragma unroll
;                         for (int e = 0; e < 8; ++e) v[e] = v[e] * sigm(v[e]);
;                     } else if (g == 6 || g == 7) {
; #pragma unroll
;                         for (int e = 0; e < 8; ++e) v[e] = sigm(v[e]);
;                     }
;                     *(GAS v4u*)(dstb + row * DM + cb + bj * 32) = pack8(v);
.LBB0_297:
	v_lshlrev_b64 v[138:139], 11, v[138:139]
	v_lshl_add_u64 v[134:135], v[134:135], 0, v[138:139]
	s_and_b64 vcc, exec, s[8:9]
	s_mov_b64 s[8:9], -1
	v_readlane_b32 s89, v255, 8
	v_cvt_pk_bf16_f32 v166, v166, v167
	v_cvt_pk_bf16_f32 v167, v142, v143
	v_cvt_pk_bf16_f32 v168, v144, v145
	v_cvt_pk_bf16_f32 v169, v140, v141
	ds_write_b128 v232, v[166:169]
	s_cbranch_vccnz .LBB0_304
	s_and_b64 vcc, exec, s[6:7]
	s_cbranch_vccnz .LBB0_301
	s_andn2_b64 vcc, exec, s[86:87]
	s_cbranch_vccnz .LBB0_363
	v_mul_f32_e32 v131, 0xbfb8aa3b, v6
	v_exp_f32_e32 v131, v131
	v_mul_f32_e32 v138, 0xbfb8aa3b, v7
	v_mul_f32_e32 v139, 0xbfb8aa3b, v8
	v_exp_f32_e32 v140, v138
	v_exp_f32_e32 v141, v139
	v_add_f32_e32 v131, 1.0, v131
	v_rcp_f32_e32 v138, v131
	v_add_f32_e32 v131, 1.0, v140
	v_mul_f32_e32 v140, 0xbfb8aa3b, v9
	v_rcp_f32_e32 v139, v131
	v_add_f32_e32 v131, 1.0, v141
	v_exp_f32_e32 v141, v140
	v_mul_f32_e32 v140, 0xbfb8aa3b, v2
	v_exp_f32_e32 v142, v140
	v_rcp_f32_e32 v140, v131
	v_add_f32_e32 v131, 1.0, v141
	v_rcp_f32_e32 v141, v131
	v_add_f32_e32 v131, 1.0, v142
	v_mul_f32_e32 v143, 0xbfb8aa3b, v4
	v_rcp_f32_e32 v142, v131
	v_mul_f32_e32 v131, 0xbfb8aa3b, v3
	v_exp_f32_e32 v143, v143
	v_mul_f32_e32 v144, 0xbfb8aa3b, v5
	v_exp_f32_e32 v131, v131
	v_exp_f32_e32 v144, v144
	v_add_f32_e32 v143, 1.0, v143
	v_rcp_f32_e32 v166, v143
	v_add_f32_e32 v131, 1.0, v131
	v_add_f32_e32 v143, 1.0, v144
	v_rcp_f32_e32 v167, v143
	v_rcp_f32_e32 v143, v131
	v_pk_mul_f32 v[140:141], v[8:9], v[140:141]
	v_pk_mul_f32 v[144:145], v[6:7], v[138:139]
	v_pk_mul_f32 v[138:139], v[4:5], v[166:167]
	v_pk_mul_f32 v[142:143], v[2:3], v[142:143]
	s_cbranch_execz .LBB0_302
	s_branch .LBB0_303

; #define GAS __attribute__((address_space(1)))
;     __device__ __forceinline__ bool operator()(pg8::f32x4 (&acc)[2][2][4][2], const pg8::Unit& u, int wr, int wc, int fr, int fq) const {
;     ...
;                     } else if (g == 4) {
;                         GAS f32x4* o = (GAS f32x4*)(vout + row * DM + cb + bj * 32); o[0] = (f32x4){v[0], v[1], v[2], v[3]}; o[1] = (f32x4){v[4], v[5], v[6], v[7]};
.LBB0_302:
	ds_write_b128 v235, v[6:9]
	ds_write_b128 v235, v[2:5] offset:16
	ds_read_b128 v[238:241], v236
	ds_read_b128 v[242:245], v236 offset:1152
	v_lshl_add_u64 v[246:247], v[132:133], 0, v[252:253]
	v_lshl_add_u64 v[248:249], v[246:247], 0, s[100:101]
	s_waitcnt lgkmcnt(0)
	global_store_dwordx4 v[246:247], v[238:241], off offset:128
	global_store_dwordx4 v[248:249], v[242:245], off offset:128

; #define GAS __attribute__((address_space(1)))
; __device__ __forceinline__ float sigm(float v) { return __builtin_amdgcn_rcpf(1.f + __builtin_amdgcn_exp2f(-LOG2E * v)); }
; __device__ __forceinline__ v4u pack8(const float* v) { v4u w; w.x = pk2(v[0], v[1]); w.y = pk2(v[2], v[3]); w.z = pk2(v[4], v[5]); w.w = pk2(v[6], v[7]); return w; }
;     __device__ __forceinline__ bool operator()(pg8::f32x4 (&acc)[2][2][4][2], const pg8::Unit& u, int wr, int wc, int fr, int fq) const {
;     ...
; #pragma unroll
;         for (int ai = 0; ai < 2; ++ai)
; #pragma unroll
;             for (int m = 0; m < 4; ++m) {
;                 const int rowi = row0 + ai * 128 + m * 16; const size_t row = (size_t)rowi;
; #pragma unroll
;                 for (int bj = 0; bj < 2; ++bj) {
;                     float v[8];
; #pragma unroll
;                     for (int e = 0; e < 8; ++e) v[e] = acc[ai][bj][m][e >> 2][e & 3];
;                     if (g == 0) {
;                         const int t = smp ? (rowi & 63) : (rowi & 2047); const int T = smp ? 64 : 2048;
;                         if (t >= T - 3) { const int b = smp ? ((rowi - MP) >> 6) : (rowi >> 11);
;                             GAS f32x4* o = (GAS f32x4*)(out + (smp ? O_CS : O_CP) + (size_t)(b * 3 + (t - (T - 3))) * DM + cb + bj * 32);
;                             o[0] = (f32x4){v[0], v[1], v[2], v[3]}; o[1] = (f32x4){v[4], v[5], v[6], v[7]}; }
;                     } else if (g == 4) {
;                         GAS f32x4* o = (GAS f32x4*)(vout + row * DM + cb + bj * 32); o[0] = (f32x4){v[0], v[1], v[2], v[3]}; o[1] = (f32x4){v[4], v[5], v[6], v[7]};
;                     } else if (g == 1 || g == 5) {
; #pragma unroll
;                         for (int e = 0; e < 8; ++e) v[e] = v[e] * sigm(v[e]);
;                     } else if (g == 6 || g == 7) {
; #pragma unroll
;                         for (int e = 0; e < 8; ++e) v[e] = sigm(v[e]);
;                     }
;                     *(GAS v4u*)(dstb + row * DM + cb + bj * 32) = pack8(v);
.LBB0_308:
	v_cvt_pk_bf16_f32 v130, v144, v145
	v_cvt_pk_bf16_f32 v131, v140, v141
	v_cvt_pk_bf16_f32 v132, v142, v143
	v_cvt_pk_bf16_f32 v133, v138, v139
	ds_write_b128 v233, v[130:133]
	ds_read_b128 v[238:241], v234
	ds_read_b128 v[242:245], v234 offset:8192
	v_lshl_add_u64 v[246:247], v[134:135], 0, v[250:251]
	v_lshl_add_u64 v[248:249], v[246:247], 0, s[98:99]
	s_waitcnt lgkmcnt(0)
	global_store_dwordx4 v[246:247], v[238:241], off
	global_store_dwordx4 v[248:249], v[242:245], off
	s_mov_b64 s[6:7], 0

; #define GAS __attribute__((address_space(1)))
; __device__ __forceinline__ v4u pack8(const float* v) { v4u w; w.x = pk2(v[0], v[1]); w.y = pk2(v[2], v[3]); w.z = pk2(v[4], v[5]); w.w = pk2(v[6], v[7]); return w; }
;     __device__ __forceinline__ bool operator()(pg8::f32x4 (&acc)[2][2][4][2], const pg8::Unit& u, int wr, int wc, int fr, int fq) const {
;         const int g = u.pn >> 2;
;         const int cb = (u.pn & 3) * 256 + wc * 64 + fq * 8;
;         const int row0 = u.pm * 256 + wr * 64 + fr;
;         const bool smp = u.pm >= 256;
;         if (g == 2 || g == 3) {
;             const float* gn = (g == 2) ? qg : kg; const float sc = (g == 2) ? QSCALE : 1.f;
;             float gv[2][8];
; #pragma unroll
;             for (int bj = 0; bj < 2; ++bj)
; #pragma unroll
;                 for (int e = 0; e < 8; ++e) gv[bj][e] = gn[bj * 32 + fq * 8 + e] * sc;
;             bf16* dstb = (bf16*)(ws + (g == 2 ? WS_Q : WS_K));
;             float* kout = smp ? out + O_KS - (size_t)MP * DM : out + O_KP;
; #pragma unroll
;             for (int ai = 0; ai < 2; ++ai)
; #pragma unroll
;                 for (int m = 0; m < 4; ++m) {
;                     const size_t row = (size_t)(row0 + ai * 128 + m * 16);
;                     float ss = 0.f;
; #pragma unroll
;                     for (int bj = 0; bj < 2; ++bj)
; #pragma unroll
;                         for (int n = 0; n < 2; ++n) { const pg8::f32x4 a = acc[ai][bj][m][n]; ss += (a.x * a.x + a.y * a.y) + (a.z * a.z + a.w * a.w); }
;                     ss += __shfl_xor(ss, 16); ss += __shfl_xor(ss, 32);
;                     const float rinv = 1.f / sqrtf(ss * (1.f / 64.f) + EPS);
; #pragma unroll
;                     for (int bj = 0; bj < 2; ++bj) {
;                         float v[8];
; #pragma unroll
;                         for (int e = 0; e < 8; ++e) v[e] = acc[ai][bj][m][e >> 2][e & 3] * rinv * gv[bj][e];
;                         *(GAS v4u*)(dstb + row * DM + cb + bj * 32) = pack8(v);
;                         if (g == 3) { GAS f32x4* o = (GAS f32x4*)(kout + row * DM + cb + bj * 32); o[0] = (f32x4){v[0], v[1], v[2], v[3]}; o[1] = (f32x4){v[4], v[5], v[6], v[7]}; }
;                     }
.LBB0_312:
	s_andn2_b64 vcc, exec, s[6:7]
	s_cbranch_vccnz .LBB0_345
	s_cmp_eq_u32 s29, 3
	s_cselect_b64 s[6:7], -1, 0
	s_cmp_eq_u32 s29, 2
	s_cselect_b64 vcc, -1, 0
	s_and_b64 s[8:9], vcc, exec
	s_cselect_b32 s8, s66, s36
	s_cselect_b32 s9, s67, s37
	global_load_dwordx4 v[134:137], v183, s[8:9]
	global_load_dwordx4 v[130:133], v183, s[8:9] offset:16
	v_and_b32_e32 v167, 64, v187
	v_xor_b32_e32 v165, 16, v187
	v_add_u32_e32 v191, 64, v167
	v_cndmask_b32_e32 v170, 1.0, v186, vcc
	v_pk_mul_f32 v[138:139], v[128:129], v[128:129]
	v_pk_mul_f32 v[140:141], v[126:127], v[126:127]
	v_pk_mul_f32 v[142:143], v[124:125], v[124:125]
	v_pk_mul_f32 v[144:145], v[122:123], v[122:123]
	v_mul_f32_e32 v166, v119, v119
	v_cmp_lt_i32_e32 vcc, v165, v191
	v_mul_f32_e32 v188, v116, v116
	v_pk_mov_b32 v[174:175], v[140:141], v[138:139] op_sel:[1,0]
	v_mov_b32_e32 v141, v139
	v_pk_mov_b32 v[138:139], v[144:145], v[142:143] op_sel:[1,0]
	v_mov_b32_e32 v145, v143
	v_pk_fma_f32 v[166:167], v[118:119], v[118:119], v[166:167] op_sel_hi:[1,1,0]
	v_cndmask_b32_e32 v142, v187, v165, vcc
	v_pk_add_f32 v[174:175], v[174:175], v[140:141]
	v_pk_add_f32 v[176:177], v[138:139], v[144:145]
	v_mov_b32_e32 v167, v188
	v_lshlrev_b32_e32 v188, 2, v142
	global_load_dwordx4 v[138:141], v183, s[8:9] offset:144
	global_load_dwordx4 v[142:145], v183, s[8:9] offset:128
	v_mul_f32_e32 v168, v121, v121
	v_mul_f32_e32 v173, v114, v114
	v_mul_f32_e32 v189, v115, v115
	v_mul_f32_e32 v190, v117, v117
	v_pk_fma_f32 v[168:169], v[120:121], v[120:121], v[168:169] op_sel_hi:[1,1,0]
	v_pk_add_f32 v[174:175], v[174:175], v[174:175] op_sel:[0,1] op_sel_hi:[1,0]
	v_pk_add_f32 v[176:177], v[176:177], v[176:177] op_sel:[0,1] op_sel_hi:[1,0]
	v_mov_b32_e32 v169, v190
	v_mov_b32_e32 v175, v173
	v_mov_b32_e32 v177, v189
	v_pk_add_f32 v[166:167], v[166:167], v[168:169]
	v_pk_add_f32 v[168:169], v[174:175], v[176:177]
	v_xor_b32_e32 v171, 32, v187
	v_pk_add_f32 v[166:167], v[168:169], v[166:167]
	v_cmp_lt_i32_e32 vcc, v171, v191
	v_add_f32_e32 v165, v166, v167
	ds_bpermute_b32 v166, v188, v165
	v_cndmask_b32_e32 v167, v187, v171, vcc
	v_lshlrev_b32_e32 v189, 2, v167
	s_mov_b32 s2, 0x1ac00000
	s_cselect_b32 s2, s2, 0x23000000
	s_waitcnt lgkmcnt(0)
	v_add_f32_e32 v165, v165, v166
	ds_bpermute_b32 v168, v189, v165
	s_add_u32 s8, s74, s2
	v_lshlrev_b32_e32 v156, 1, v172
	s_addc_u32 s9, s75, 0
	v_lshl_add_u64 v[166:167], s[8:9], 0, v[156:157]
	s_waitcnt lgkmcnt(0)
	v_add_f32_e32 v156, v165, v168
	v_fmamk_f32 v156, v156, 0x3c800000, v184
	v_mul_f32_e32 v165, 0x4f800000, v156
	v_cmp_gt_f32_e32 vcc, s61, v156
	s_and_b64 s[4:5], s[4:5], exec
	s_mov_b32 s2, 0x20880000
	v_cndmask_b32_e32 v156, v156, v165, vcc
	v_sqrt_f32_e32 v165, v156
	s_cselect_b32 s2, s2, 0x10800000
	s_add_u32 s8, s72, s2
	s_addc_u32 s9, s73, 0
	v_add_u32_e32 v168, -1, v165
	v_add_u32_e32 v169, 1, v165
	v_fma_f32 v171, -v168, v165, v156
	v_fma_f32 v173, -v169, v165, v156
	v_cmp_ge_f32_e64 s[4:5], 0, v171
	s_cmp_lg_u32 s29, 3
	s_nop 0
	v_cndmask_b32_e64 v165, v165, v168, s[4:5]
	v_cmp_lt_f32_e64 s[4:5], 0, v173
	s_nop 1
	v_cndmask_b32_e64 v165, v165, v169, s[4:5]
	v_mul_f32_e32 v168, 0x37800000, v165
	v_cndmask_b32_e32 v165, v165, v168, vcc
	v_cmp_class_f32_e32 vcc, v156, v185
	s_nop 1
	v_cndmask_b32_e32 v171, v165, v156, vcc
	v_div_scale_f32 v173, s[4:5], v171, v171, 1.0
	v_rcp_f32_e32 v174, v173
	v_lshlrev_b32_e32 v156, 2, v172
	s_waitcnt vmcnt(0)
	v_pk_mul_f32 v[168:169], v[170:171], v[134:135] op_sel_hi:[0,1]
	v_pk_mul_f32 v[134:135], v[170:171], v[130:131] op_sel_hi:[0,1]
	v_pk_mul_f32 v[130:131], v[170:171], v[132:133] op_sel_hi:[0,1]
	v_lshl_add_u64 v[132:133], s[8:9], 0, v[156:157]
	v_fma_f32 v156, -v173, v174, 1.0
	v_fmac_f32_e32 v174, v156, v174
	v_div_scale_f32 v156, vcc, 1.0, v171, 1.0
	v_mul_f32_e32 v172, v156, v174
	v_fma_f32 v175, -v173, v172, v156
	v_fmac_f32_e32 v172, v175, v174
	v_fma_f32 v156, -v173, v172, v156
	v_ashrrev_i32_e32 v165, 31, v164
	v_div_fmas_f32 v156, v156, v174, v172
	v_div_fixup_f32 v176, v156, v171, 1.0
	v_lshlrev_b64 v[172:173], 11, v[164:165]
	v_pk_mul_f32 v[136:137], v[170:171], v[136:137] op_sel_hi:[0,1]
	v_lshl_add_u64 v[174:175], v[166:167], 0, v[172:173]
	v_lshlrev_b64 v[172:173], 12, v[164:165]
	v_pk_mul_f32 v[126:127], v[126:127], v[176:177] op_sel_hi:[1,0]
	v_pk_mul_f32 v[128:129], v[128:129], v[176:177] op_sel_hi:[1,0]
	v_pk_mul_f32 v[122:123], v[122:123], v[176:177] op_sel_hi:[1,0]
	v_pk_mul_f32 v[124:125], v[124:125], v[176:177] op_sel_hi:[1,0]
	v_lshl_add_u64 v[172:173], v[132:133], 0, v[172:173]
	v_pk_mul_f32 v[126:127], v[168:169], v[126:127]
	v_pk_mul_f32 v[128:129], v[136:137], v[128:129]
	v_pk_mul_f32 v[122:123], v[134:135], v[122:123]
	v_pk_mul_f32 v[124:125], v[130:131], v[124:125]
	v_cvt_pk_bf16_f32 v190, v126, v127
	v_cvt_pk_bf16_f32 v191, v128, v129
	v_cvt_pk_bf16_f32 v192, v122, v123
	s_nop 0
	v_cvt_pk_bf16_f32 v193, v124, v125
	ds_write_b128 v232, v[190:193]
	s_cbranch_scc1 .LBB0_315
	ds_write_b128 v235, v[126:129]
	ds_write_b128 v235, v[122:125] offset:16
	ds_read_b128 v[238:241], v236
	ds_read_b128 v[242:245], v236 offset:1152
	v_lshl_add_u64 v[246:247], v[172:173], 0, v[252:253]
	v_lshl_add_u64 v[248:249], v[246:247], 0, s[100:101]
	s_waitcnt lgkmcnt(0)
	global_store_dwordx4 v[246:247], v[238:241], off
	global_store_dwordx4 v[248:249], v[242:245], off
; #define GAS __attribute__((address_space(1)))
; __device__ __forceinline__ v4u pack8(const float* v) { v4u w; w.x = pk2(v[0], v[1]); w.y = pk2(v[2], v[3]); w.z = pk2(v[4], v[5]); w.w = pk2(v[6], v[7]); return w; }
;     __device__ __forceinline__ bool operator()(pg8::f32x4 (&acc)[2][2][4][2], const pg8::Unit& u, int wr, int wc, int fr, int fq) const {
;     ...
; #pragma unroll
;             for (int ai = 0; ai < 2; ++ai)
; #pragma unroll
;                 for (int m = 0; m < 4; ++m) {
;                     const size_t row = (size_t)(row0 + ai * 128 + m * 16);
;                     float ss = 0.f;
; #pragma unroll
;                     for (int bj = 0; bj < 2; ++bj)
; #pragma unroll
;                         for (int n = 0; n < 2; ++n) { const pg8::f32x4 a = acc[ai][bj][m][n]; ss += (a.x * a.x + a.y * a.y) + (a.z * a.z + a.w * a.w); }
;                     ss += __shfl_xor(ss, 16); ss += __shfl_xor(ss, 32);
;                     const float rinv = 1.f / sqrtf(ss * (1.f / 64.f) + EPS);
; #pragma unroll
;                     for (int bj = 0; bj < 2; ++bj) {
;                         float v[8];
; #pragma unroll
;                         for (int e = 0; e < 8; ++e) v[e] = acc[ai][bj][m][e >> 2][e & 3] * rinv * gv[bj][e];
;                         *(GAS v4u*)(dstb + row * DM + cb + bj * 32) = pack8(v);
;                         if (g == 3) { GAS f32x4* o = (GAS f32x4*)(kout + row * DM + cb + bj * 32); o[0] = (f32x4){v[0], v[1], v[2], v[3]}; o[1] = (f32x4){v[4], v[5], v[6], v[7]}; }
;                     }
.LBB0_315:
	v_mov_b32_e32 v171, v170
	v_mov_b32_e32 v177, v176
	v_pk_mul_f32 v[128:129], v[170:171], v[142:143]
	v_pk_mul_f32 v[126:127], v[170:171], v[144:145]
	v_pk_mul_f32 v[124:125], v[170:171], v[138:139]
	v_pk_mul_f32 v[122:123], v[170:171], v[140:141]
	v_pk_mul_f32 v[118:119], v[118:119], v[176:177]
	v_pk_mul_f32 v[120:121], v[120:121], v[176:177]
	v_pk_mul_f32 v[114:115], v[114:115], v[176:177]
	v_pk_mul_f32 v[116:117], v[116:117], v[176:177]
	v_cndmask_b32_e64 v142, 0, 1, s[6:7]
	v_pk_mul_f32 v[118:119], v[128:129], v[118:119]
	v_pk_mul_f32 v[120:121], v[126:127], v[120:121]
	v_pk_mul_f32 v[114:115], v[124:125], v[114:115]
	v_pk_mul_f32 v[116:117], v[122:123], v[116:117]
	v_cmp_ne_u32_e64 s[4:5], 1, v142
	s_andn2_b64 vcc, exec, s[6:7]
	v_cvt_pk_bf16_f32 v138, v118, v119
	v_cvt_pk_bf16_f32 v139, v120, v121
	v_cvt_pk_bf16_f32 v140, v114, v115
	v_cvt_pk_bf16_f32 v141, v116, v117
	ds_write_b128 v233, v[138:141]
	ds_read_b128 v[238:241], v234
	ds_read_b128 v[242:245], v234 offset:8192
	v_lshl_add_u64 v[246:247], v[174:175], 0, v[250:251]
	v_lshl_add_u64 v[248:249], v[246:247], 0, s[98:99]
	s_waitcnt lgkmcnt(0)
	global_store_dwordx4 v[246:247], v[238:241], off
	global_store_dwordx4 v[248:249], v[242:245], off
	s_cbranch_vccnz .LBB0_317
	ds_write_b128 v235, v[118:121]
	ds_write_b128 v235, v[114:117] offset:16
	ds_read_b128 v[238:241], v236
	ds_read_b128 v[242:245], v236 offset:1152
	v_lshl_add_u64 v[246:247], v[172:173], 0, v[252:253]
	v_lshl_add_u64 v[248:249], v[246:247], 0, s[100:101]
	s_waitcnt lgkmcnt(0)
	global_store_dwordx4 v[246:247], v[238:241], off offset:128
	global_store_dwordx4 v[248:249], v[242:245], off offset:128
.LBB0_317:
	s_nop 1
	v_pk_mul_f32 v[114:115], v[112:113], v[112:113]
	v_pk_mul_f32 v[116:117], v[110:111], v[110:111]
	s_nop 0
	v_pk_mov_b32 v[118:119], v[116:117], v[114:115] op_sel:[1,0]
	v_mov_b32_e32 v117, v115
	v_pk_add_f32 v[114:115], v[118:119], v[116:117]
	v_pk_mul_f32 v[116:117], v[108:109], v[108:109]
	v_pk_mul_f32 v[118:119], v[106:107], v[106:107]
	v_pk_add_f32 v[114:115], v[114:115], v[114:115] op_sel:[0,1] op_sel_hi:[1,0]
	v_pk_mov_b32 v[120:121], v[118:119], v[116:117] op_sel:[1,0]
	v_mov_b32_e32 v119, v117
	v_pk_add_f32 v[116:117], v[120:121], v[118:119]
	v_mul_f32_e32 v118, v98, v98
	v_mul_f32_e32 v119, v99, v99
	v_pk_add_f32 v[116:117], v[116:117], v[116:117] op_sel:[0,1] op_sel_hi:[1,0]
	v_mov_b32_e32 v115, v118
	v_mov_b32_e32 v117, v119
	v_pk_add_f32 v[114:115], v[114:115], v[116:117]
	v_mul_f32_e32 v116, v103, v103
	v_mul_f32_e32 v118, v105, v105
	v_mul_f32_e32 v120, v100, v100
	v_mul_f32_e32 v121, v101, v101
	v_pk_fma_f32 v[116:117], v[102:103], v[102:103], v[116:117] op_sel_hi:[1,1,0]
	v_pk_fma_f32 v[118:119], v[104:105], v[104:105], v[118:119] op_sel_hi:[1,1,0]
	v_mov_b32_e32 v117, v120
	v_mov_b32_e32 v119, v121
	v_pk_add_f32 v[116:117], v[116:117], v[118:119]
	s_nop 0
	v_pk_add_f32 v[114:115], v[114:115], v[116:117]
	s_nop 0
	v_add_f32_e32 v114, v114, v115
	ds_bpermute_b32 v115, v188, v114
	s_waitcnt lgkmcnt(0)
	v_add_f32_e32 v114, v114, v115
	ds_bpermute_b32 v115, v189, v114
	s_waitcnt lgkmcnt(0)
	v_add_f32_e32 v114, v114, v115
	v_fmamk_f32 v114, v114, 0x3c800000, v184
	v_mul_f32_e32 v115, 0x4f800000, v114
	v_cmp_gt_f32_e32 vcc, s61, v114
	s_nop 1
	v_cndmask_b32_e32 v114, v114, v115, vcc
	v_sqrt_f32_e32 v115, v114
	s_nop 0
	v_add_u32_e32 v116, -1, v115
	v_fma_f32 v117, -v116, v115, v114
	v_cmp_ge_f32_e64 s[6:7], 0, v117
	v_add_u32_e32 v117, 1, v115
	s_nop 0
	v_cndmask_b32_e64 v116, v115, v116, s[6:7]
	v_fma_f32 v115, -v117, v115, v114
	v_cmp_lt_f32_e64 s[6:7], 0, v115
	s_nop 1
	v_cndmask_b32_e64 v115, v116, v117, s[6:7]
	v_mul_f32_e32 v116, 0x37800000, v115
	v_cndmask_b32_e32 v115, v115, v116, vcc
	v_cmp_class_f32_e32 vcc, v114, v185
	s_nop 1
	v_cndmask_b32_e32 v116, v115, v114, vcc
	v_div_scale_f32 v117, s[6:7], v116, v116, 1.0
	v_rcp_f32_e32 v118, v117
	v_or_b32_e32 v114, 16, v164
	v_ashrrev_i32_e32 v115, 31, v114
	v_fma_f32 v119, -v117, v118, 1.0
	v_fmac_f32_e32 v118, v119, v118
	v_div_scale_f32 v119, vcc, 1.0, v116, 1.0
	v_mul_f32_e32 v120, v119, v118
	v_fma_f32 v121, -v117, v120, v119
	v_fmac_f32_e32 v120, v121, v118
	v_fma_f32 v117, -v117, v120, v119
	v_div_fmas_f32 v117, v117, v118, v120
	v_div_fixup_f32 v118, v117, v116, 1.0
	v_lshlrev_b64 v[116:117], 11, v[114:115]
	v_lshlrev_b64 v[114:115], 12, v[114:115]
	v_pk_mul_f32 v[110:111], v[110:111], v[118:119] op_sel_hi:[1,0]
	v_pk_mul_f32 v[112:113], v[112:113], v[118:119] op_sel_hi:[1,0]
	v_pk_mul_f32 v[106:107], v[106:107], v[118:119] op_sel_hi:[1,0]
	v_pk_mul_f32 v[108:109], v[108:109], v[118:119] op_sel_hi:[1,0]
	v_lshl_add_u64 v[116:117], v[166:167], 0, v[116:117]
	v_lshl_add_u64 v[114:115], v[132:133], 0, v[114:115]
	v_pk_mul_f32 v[110:111], v[168:169], v[110:111]
	v_pk_mul_f32 v[112:113], v[136:137], v[112:113]
	v_pk_mul_f32 v[106:107], v[134:135], v[106:107]
	v_pk_mul_f32 v[108:109], v[130:131], v[108:109]
	s_and_b64 vcc, exec, s[4:5]
	v_cvt_pk_bf16_f32 v138, v110, v111
	v_cvt_pk_bf16_f32 v139, v112, v113
	v_cvt_pk_bf16_f32 v140, v106, v107
	v_cvt_pk_bf16_f32 v141, v108, v109
	ds_write_b128 v232, v[138:141]
	s_cbranch_vccnz .LBB0_319
	ds_write_b128 v235, v[110:113]
	ds_write_b128 v235, v[106:109] offset:16
	ds_read_b128 v[238:241], v236
	ds_read_b128 v[242:245], v236 offset:1152
	v_lshl_add_u64 v[246:247], v[114:115], 0, v[252:253]
	v_lshl_add_u64 v[248:249], v[246:247], 0, s[100:101]
	s_waitcnt lgkmcnt(0)
	global_store_dwordx4 v[246:247], v[238:241], off
	global_store_dwordx4 v[248:249], v[242:245], off
; #define GAS __attribute__((address_space(1)))
; __device__ __forceinline__ v4u pack8(const float* v) { v4u w; w.x = pk2(v[0], v[1]); w.y = pk2(v[2], v[3]); w.z = pk2(v[4], v[5]); w.w = pk2(v[6], v[7]); return w; }
;     __device__ __forceinline__ bool operator()(pg8::f32x4 (&acc)[2][2][4][2], const pg8::Unit& u, int wr, int wc, int fr, int fq) const {
;     ...
; #pragma unroll
;             for (int ai = 0; ai < 2; ++ai)
; #pragma unroll
;                 for (int m = 0; m < 4; ++m) {
;                     const size_t row = (size_t)(row0 + ai * 128 + m * 16);
;                     float ss = 0.f;
; #pragma unroll
;                     for (int bj = 0; bj < 2; ++bj)
; #pragma unroll
;                         for (int n = 0; n < 2; ++n) { const pg8::f32x4 a = acc[ai][bj][m][n]; ss += (a.x * a.x + a.y * a.y) + (a.z * a.z + a.w * a.w); }
;                     ss += __shfl_xor(ss, 16); ss += __shfl_xor(ss, 32);
;                     const float rinv = 1.f / sqrtf(ss * (1.f / 64.f) + EPS);
; #pragma unroll
;                     for (int bj = 0; bj < 2; ++bj) {
;                         float v[8];
; #pragma unroll
;                         for (int e = 0; e < 8; ++e) v[e] = acc[ai][bj][m][e >> 2][e & 3] * rinv * gv[bj][e];
;                         *(GAS v4u*)(dstb + row * DM + cb + bj * 32) = pack8(v);
;                         if (g == 3) { GAS f32x4* o = (GAS f32x4*)(kout + row * DM + cb + bj * 32); o[0] = (f32x4){v[0], v[1], v[2], v[3]}; o[1] = (f32x4){v[4], v[5], v[6], v[7]}; }
;                     }
.LBB0_319:
	v_mov_b32_e32 v119, v118
	v_pk_mul_f32 v[102:103], v[102:103], v[118:119]
	v_pk_mul_f32 v[104:105], v[104:105], v[118:119]
	v_pk_mul_f32 v[98:99], v[98:99], v[118:119]
	v_pk_mul_f32 v[100:101], v[100:101], v[118:119]
	v_pk_mul_f32 v[102:103], v[128:129], v[102:103]
	v_pk_mul_f32 v[104:105], v[126:127], v[104:105]
	v_pk_mul_f32 v[98:99], v[124:125], v[98:99]
	v_pk_mul_f32 v[100:101], v[122:123], v[100:101]
	s_and_b64 vcc, exec, s[4:5]
	v_cvt_pk_bf16_f32 v106, v102, v103
	v_cvt_pk_bf16_f32 v107, v104, v105
	v_cvt_pk_bf16_f32 v108, v98, v99
	v_cvt_pk_bf16_f32 v109, v100, v101
	ds_write_b128 v233, v[106:109]
	ds_read_b128 v[238:241], v234
	ds_read_b128 v[242:245], v234 offset:8192
	v_lshl_add_u64 v[246:247], v[116:117], 0, v[250:251]
	v_lshl_add_u64 v[248:249], v[246:247], 0, s[98:99]
	s_waitcnt lgkmcnt(0)
	global_store_dwordx4 v[246:247], v[238:241], off
	global_store_dwordx4 v[248:249], v[242:245], off
	s_cbranch_vccnz .LBB0_321
	ds_write_b128 v235, v[102:105]
	ds_write_b128 v235, v[98:101] offset:16
	ds_read_b128 v[238:241], v236
	ds_read_b128 v[242:245], v236 offset:1152
	v_lshl_add_u64 v[246:247], v[114:115], 0, v[252:253]
	v_lshl_add_u64 v[248:249], v[246:247], 0, s[100:101]
	s_waitcnt lgkmcnt(0)
	global_store_dwordx4 v[246:247], v[238:241], off offset:128
	global_store_dwordx4 v[248:249], v[242:245], off offset:128
.LBB0_321:
	s_nop 1
	v_pk_mul_f32 v[98:99], v[96:97], v[96:97]
	v_pk_mul_f32 v[100:101], v[94:95], v[94:95]
	s_nop 0
	v_pk_mov_b32 v[102:103], v[100:101], v[98:99] op_sel:[1,0]
	v_mov_b32_e32 v101, v99
	v_pk_add_f32 v[98:99], v[102:103], v[100:101]
	v_pk_mul_f32 v[100:101], v[92:93], v[92:93]
	v_pk_mul_f32 v[102:103], v[90:91], v[90:91]
	v_pk_add_f32 v[98:99], v[98:99], v[98:99] op_sel:[0,1] op_sel_hi:[1,0]
	v_pk_mov_b32 v[104:105], v[102:103], v[100:101] op_sel:[1,0]
	v_mov_b32_e32 v103, v101
	v_pk_add_f32 v[100:101], v[104:105], v[102:103]
	v_mul_f32_e32 v102, v82, v82
	v_mul_f32_e32 v103, v83, v83
	v_pk_add_f32 v[100:101], v[100:101], v[100:101] op_sel:[0,1] op_sel_hi:[1,0]
	v_mov_b32_e32 v99, v102
	v_mov_b32_e32 v101, v103
	v_pk_add_f32 v[98:99], v[98:99], v[100:101]
	v_mul_f32_e32 v100, v87, v87
	v_mul_f32_e32 v102, v89, v89
	v_mul_f32_e32 v104, v84, v84
	v_mul_f32_e32 v105, v85, v85
	v_pk_fma_f32 v[100:101], v[86:87], v[86:87], v[100:101] op_sel_hi:[1,1,0]
	v_pk_fma_f32 v[102:103], v[88:89], v[88:89], v[102:103] op_sel_hi:[1,1,0]
	v_mov_b32_e32 v101, v104
	v_mov_b32_e32 v103, v105
	v_pk_add_f32 v[100:101], v[100:101], v[102:103]
	s_nop 0
	v_pk_add_f32 v[98:99], v[98:99], v[100:101]
	s_nop 0
	v_add_f32_e32 v98, v98, v99
	ds_bpermute_b32 v99, v188, v98
	s_waitcnt lgkmcnt(0)
	v_add_f32_e32 v98, v98, v99
	ds_bpermute_b32 v99, v189, v98
	s_waitcnt lgkmcnt(0)
	v_add_f32_e32 v98, v98, v99
	v_fmamk_f32 v98, v98, 0x3c800000, v184
	v_mul_f32_e32 v99, 0x4f800000, v98
	v_cmp_gt_f32_e32 vcc, s61, v98
	s_nop 1
	v_cndmask_b32_e32 v98, v98, v99, vcc
	v_sqrt_f32_e32 v99, v98
	s_nop 0
	v_add_u32_e32 v100, -1, v99
	v_fma_f32 v101, -v100, v99, v98
	v_cmp_ge_f32_e64 s[6:7], 0, v101
	v_add_u32_e32 v101, 1, v99
	s_nop 0
	v_cndmask_b32_e64 v100, v99, v100, s[6:7]
	v_fma_f32 v99, -v101, v99, v98
	v_cmp_lt_f32_e64 s[6:7], 0, v99
	s_nop 1
	v_cndmask_b32_e64 v99, v100, v101, s[6:7]
	v_mul_f32_e32 v100, 0x37800000, v99
	v_cndmask_b32_e32 v99, v99, v100, vcc
	v_cmp_class_f32_e32 vcc, v98, v185
	s_nop 1
	v_cndmask_b32_e32 v100, v99, v98, vcc
	v_div_scale_f32 v101, s[6:7], v100, v100, 1.0
	v_rcp_f32_e32 v102, v101
	v_or_b32_e32 v98, 32, v164
	v_ashrrev_i32_e32 v99, 31, v98
	v_fma_f32 v103, -v101, v102, 1.0
	v_fmac_f32_e32 v102, v103, v102
	v_div_scale_f32 v103, vcc, 1.0, v100, 1.0
	v_mul_f32_e32 v104, v103, v102
	v_fma_f32 v105, -v101, v104, v103
	v_fmac_f32_e32 v104, v105, v102
	v_fma_f32 v101, -v101, v104, v103
	v_div_fmas_f32 v101, v101, v102, v104
	v_div_fixup_f32 v102, v101, v100, 1.0
	v_lshlrev_b64 v[100:101], 11, v[98:99]
	v_lshlrev_b64 v[98:99], 12, v[98:99]
	v_pk_mul_f32 v[94:95], v[94:95], v[102:103] op_sel_hi:[1,0]
	v_pk_mul_f32 v[96:97], v[96:97], v[102:103] op_sel_hi:[1,0]
	v_pk_mul_f32 v[90:91], v[90:91], v[102:103] op_sel_hi:[1,0]
	v_pk_mul_f32 v[92:93], v[92:93], v[102:103] op_sel_hi:[1,0]
	v_lshl_add_u64 v[100:101], v[166:167], 0, v[100:101]
	v_lshl_add_u64 v[98:99], v[132:133], 0, v[98:99]
	v_pk_mul_f32 v[94:95], v[168:169], v[94:95]
	v_pk_mul_f32 v[96:97], v[136:137], v[96:97]
	v_pk_mul_f32 v[90:91], v[134:135], v[90:91]
	v_pk_mul_f32 v[92:93], v[130:131], v[92:93]
	s_and_b64 vcc, exec, s[4:5]
	v_cvt_pk_bf16_f32 v104, v94, v95
	v_cvt_pk_bf16_f32 v105, v96, v97
	v_cvt_pk_bf16_f32 v106, v90, v91
	v_cvt_pk_bf16_f32 v107, v92, v93
	ds_write_b128 v232, v[104:107]
	s_cbranch_vccnz .LBB0_323
	ds_write_b128 v235, v[94:97]
	ds_write_b128 v235, v[90:93] offset:16
	ds_read_b128 v[238:241], v236
	ds_read_b128 v[242:245], v236 offset:1152
	v_lshl_add_u64 v[246:247], v[98:99], 0, v[252:253]
	v_lshl_add_u64 v[248:249], v[246:247], 0, s[100:101]
	s_waitcnt lgkmcnt(0)
	global_store_dwordx4 v[246:247], v[238:241], off
	global_store_dwordx4 v[248:249], v[242:245], off
; #define GAS __attribute__((address_space(1)))
; __device__ __forceinline__ v4u pack8(const float* v) { v4u w; w.x = pk2(v[0], v[1]); w.y = pk2(v[2], v[3]); w.z = pk2(v[4], v[5]); w.w = pk2(v[6], v[7]); return w; }
;     __device__ __forceinline__ bool operator()(pg8::f32x4 (&acc)[2][2][4][2], const pg8::Unit& u, int wr, int wc, int fr, int fq) const {
;     ...
; #pragma unroll
;             for (int ai = 0; ai < 2; ++ai)
; #pragma unroll
;                 for (int m = 0; m < 4; ++m) {
;                     const size_t row = (size_t)(row0 + ai * 128 + m * 16);
;                     float ss = 0.f;
; #pragma unroll
;                     for (int bj = 0; bj < 2; ++bj)
; #pragma unroll
;                         for (int n = 0; n < 2; ++n) { const pg8::f32x4 a = acc[ai][bj][m][n]; ss += (a.x * a.x + a.y * a.y) + (a.z * a.z + a.w * a.w); }
;                     ss += __shfl_xor(ss, 16); ss += __shfl_xor(ss, 32);
;                     const float rinv = 1.f / sqrtf(ss * (1.f / 64.f) + EPS);
; #pragma unroll
;                     for (int bj = 0; bj < 2; ++bj) {
;                         float v[8];
; #pragma unroll
;                         for (int e = 0; e < 8; ++e) v[e] = acc[ai][bj][m][e >> 2][e & 3] * rinv * gv[bj][e];
;                         *(GAS v4u*)(dstb + row * DM + cb + bj * 32) = pack8(v);
;                         if (g == 3) { GAS f32x4* o = (GAS f32x4*)(kout + row * DM + cb + bj * 32); o[0] = (f32x4){v[0], v[1], v[2], v[3]}; o[1] = (f32x4){v[4], v[5], v[6], v[7]}; }
;                     }
.LBB0_323:
	v_mov_b32_e32 v103, v102
	v_pk_mul_f32 v[86:87], v[86:87], v[102:103]
	v_pk_mul_f32 v[88:89], v[88:89], v[102:103]
	v_pk_mul_f32 v[82:83], v[82:83], v[102:103]
	v_pk_mul_f32 v[84:85], v[84:85], v[102:103]
	v_pk_mul_f32 v[86:87], v[128:129], v[86:87]
	v_pk_mul_f32 v[88:89], v[126:127], v[88:89]
	v_pk_mul_f32 v[82:83], v[124:125], v[82:83]
	v_pk_mul_f32 v[84:85], v[122:123], v[84:85]
	s_and_b64 vcc, exec, s[4:5]
	v_cvt_pk_bf16_f32 v90, v86, v87
	v_cvt_pk_bf16_f32 v91, v88, v89
	v_cvt_pk_bf16_f32 v92, v82, v83
	v_cvt_pk_bf16_f32 v93, v84, v85
	ds_write_b128 v233, v[90:93]
	ds_read_b128 v[238:241], v234
	ds_read_b128 v[242:245], v234 offset:8192
	v_lshl_add_u64 v[246:247], v[100:101], 0, v[250:251]
	v_lshl_add_u64 v[248:249], v[246:247], 0, s[98:99]
	s_waitcnt lgkmcnt(0)
	global_store_dwordx4 v[246:247], v[238:241], off
	global_store_dwordx4 v[248:249], v[242:245], off
	s_cbranch_vccnz .LBB0_325
	ds_write_b128 v235, v[86:89]
	ds_write_b128 v235, v[82:85] offset:16
	ds_read_b128 v[238:241], v236
	ds_read_b128 v[242:245], v236 offset:1152
	v_lshl_add_u64 v[246:247], v[98:99], 0, v[252:253]
	v_lshl_add_u64 v[248:249], v[246:247], 0, s[100:101]
	s_waitcnt lgkmcnt(0)
	global_store_dwordx4 v[246:247], v[238:241], off offset:128
	global_store_dwordx4 v[248:249], v[242:245], off offset:128
.LBB0_325:
	s_nop 1
	v_pk_mul_f32 v[82:83], v[80:81], v[80:81]
	v_pk_mul_f32 v[84:85], v[78:79], v[78:79]
	s_nop 0
	v_pk_mov_b32 v[86:87], v[84:85], v[82:83] op_sel:[1,0]
	v_mov_b32_e32 v85, v83
	v_pk_add_f32 v[82:83], v[86:87], v[84:85]
	v_pk_mul_f32 v[84:85], v[76:77], v[76:77]
	v_pk_mul_f32 v[86:87], v[74:75], v[74:75]
	v_pk_add_f32 v[82:83], v[82:83], v[82:83] op_sel:[0,1] op_sel_hi:[1,0]
	v_pk_mov_b32 v[88:89], v[86:87], v[84:85] op_sel:[1,0]
	v_mov_b32_e32 v87, v85
	v_pk_add_f32 v[84:85], v[88:89], v[86:87]
	v_mul_f32_e32 v86, v66, v66
	v_mul_f32_e32 v87, v67, v67
	v_pk_add_f32 v[84:85], v[84:85], v[84:85] op_sel:[0,1] op_sel_hi:[1,0]
	v_mov_b32_e32 v83, v86
	v_mov_b32_e32 v85, v87
	v_pk_add_f32 v[82:83], v[82:83], v[84:85]
	v_mul_f32_e32 v84, v71, v71
	v_mul_f32_e32 v86, v73, v73
	v_mul_f32_e32 v88, v68, v68
	v_mul_f32_e32 v89, v69, v69
	v_pk_fma_f32 v[84:85], v[70:71], v[70:71], v[84:85] op_sel_hi:[1,1,0]
	v_pk_fma_f32 v[86:87], v[72:73], v[72:73], v[86:87] op_sel_hi:[1,1,0]
	v_mov_b32_e32 v85, v88
	v_mov_b32_e32 v87, v89
	v_pk_add_f32 v[84:85], v[84:85], v[86:87]
	s_nop 0
	v_pk_add_f32 v[82:83], v[82:83], v[84:85]
	s_nop 0
	v_add_f32_e32 v82, v82, v83
	ds_bpermute_b32 v83, v188, v82
	s_waitcnt lgkmcnt(0)
	v_add_f32_e32 v82, v82, v83
	ds_bpermute_b32 v83, v189, v82
	s_waitcnt lgkmcnt(0)
	v_add_f32_e32 v82, v82, v83
	v_fmamk_f32 v82, v82, 0x3c800000, v184
	v_mul_f32_e32 v83, 0x4f800000, v82
	v_cmp_gt_f32_e32 vcc, s61, v82
	s_nop 1
	v_cndmask_b32_e32 v82, v82, v83, vcc
	v_sqrt_f32_e32 v83, v82
	s_nop 0
	v_add_u32_e32 v84, -1, v83
	v_fma_f32 v85, -v84, v83, v82
	v_cmp_ge_f32_e64 s[6:7], 0, v85
	v_add_u32_e32 v85, 1, v83
	s_nop 0
	v_cndmask_b32_e64 v84, v83, v84, s[6:7]
	v_fma_f32 v83, -v85, v83, v82
	v_cmp_lt_f32_e64 s[6:7], 0, v83
	s_nop 1
	v_cndmask_b32_e64 v83, v84, v85, s[6:7]
	v_mul_f32_e32 v84, 0x37800000, v83
	v_cndmask_b32_e32 v83, v83, v84, vcc
	v_cmp_class_f32_e32 vcc, v82, v185
	s_nop 1
	v_cndmask_b32_e32 v84, v83, v82, vcc
	v_div_scale_f32 v85, s[6:7], v84, v84, 1.0
	v_rcp_f32_e32 v86, v85
	v_or_b32_e32 v82, 48, v164
	v_ashrrev_i32_e32 v83, 31, v82
	v_fma_f32 v87, -v85, v86, 1.0
	v_fmac_f32_e32 v86, v87, v86
	v_div_scale_f32 v87, vcc, 1.0, v84, 1.0
	v_mul_f32_e32 v88, v87, v86
	v_fma_f32 v89, -v85, v88, v87
	v_fmac_f32_e32 v88, v89, v86
	v_fma_f32 v85, -v85, v88, v87
	v_div_fmas_f32 v85, v85, v86, v88
	v_div_fixup_f32 v86, v85, v84, 1.0
	v_lshlrev_b64 v[84:85], 11, v[82:83]
	v_lshlrev_b64 v[82:83], 12, v[82:83]
	v_pk_mul_f32 v[78:79], v[78:79], v[86:87] op_sel_hi:[1,0]
	v_pk_mul_f32 v[80:81], v[80:81], v[86:87] op_sel_hi:[1,0]
	v_pk_mul_f32 v[74:75], v[74:75], v[86:87] op_sel_hi:[1,0]
	v_pk_mul_f32 v[76:77], v[76:77], v[86:87] op_sel_hi:[1,0]
	v_lshl_add_u64 v[84:85], v[166:167], 0, v[84:85]
	v_lshl_add_u64 v[82:83], v[132:133], 0, v[82:83]
	v_pk_mul_f32 v[78:79], v[168:169], v[78:79]
	v_pk_mul_f32 v[80:81], v[136:137], v[80:81]
	v_pk_mul_f32 v[74:75], v[134:135], v[74:75]
	v_pk_mul_f32 v[76:77], v[130:131], v[76:77]
	s_and_b64 vcc, exec, s[4:5]
	v_cvt_pk_bf16_f32 v88, v78, v79
	v_cvt_pk_bf16_f32 v89, v80, v81
	v_cvt_pk_bf16_f32 v90, v74, v75
	v_cvt_pk_bf16_f32 v91, v76, v77
	ds_write_b128 v232, v[88:91]
	s_cbranch_vccnz .LBB0_327
	ds_write_b128 v235, v[78:81]
	ds_write_b128 v235, v[74:77] offset:16
	ds_read_b128 v[238:241], v236
	ds_read_b128 v[242:245], v236 offset:1152
	v_lshl_add_u64 v[246:247], v[82:83], 0, v[252:253]
	v_lshl_add_u64 v[248:249], v[246:247], 0, s[100:101]
	s_waitcnt lgkmcnt(0)
	global_store_dwordx4 v[246:247], v[238:241], off
	global_store_dwordx4 v[248:249], v[242:245], off
.LBB0_327:
	v_mov_b32_e32 v87, v86
	v_pk_mul_f32 v[70:71], v[70:71], v[86:87]
	v_pk_mul_f32 v[72:73], v[72:73], v[86:87]
	v_pk_mul_f32 v[66:67], v[66:67], v[86:87]
	v_pk_mul_f32 v[68:69], v[68:69], v[86:87]
	v_pk_mul_f32 v[70:71], v[128:129], v[70:71]
	v_pk_mul_f32 v[72:73], v[126:127], v[72:73]
	v_pk_mul_f32 v[66:67], v[124:125], v[66:67]
	v_pk_mul_f32 v[68:69], v[122:123], v[68:69]
	s_and_b64 vcc, exec, s[4:5]
	v_cvt_pk_bf16_f32 v74, v70, v71
	v_cvt_pk_bf16_f32 v75, v72, v73
	v_cvt_pk_bf16_f32 v76, v66, v67
	v_cvt_pk_bf16_f32 v77, v68, v69
	ds_write_b128 v233, v[74:77]
	ds_read_b128 v[238:241], v234
	ds_read_b128 v[242:245], v234 offset:8192
	v_lshl_add_u64 v[246:247], v[84:85], 0, v[250:251]
	v_lshl_add_u64 v[248:249], v[246:247], 0, s[98:99]
	s_waitcnt lgkmcnt(0)
	global_store_dwordx4 v[246:247], v[238:241], off
	global_store_dwordx4 v[248:249], v[242:245], off
	s_cbranch_vccnz .LBB0_329
	ds_write_b128 v235, v[70:73]
	ds_write_b128 v235, v[66:69] offset:16
	ds_read_b128 v[238:241], v236
	ds_read_b128 v[242:245], v236 offset:1152
	v_lshl_add_u64 v[246:247], v[82:83], 0, v[252:253]
	v_lshl_add_u64 v[248:249], v[246:247], 0, s[100:101]
	s_waitcnt lgkmcnt(0)
	global_store_dwordx4 v[246:247], v[238:241], off offset:128
	global_store_dwordx4 v[248:249], v[242:245], off offset:128
; #define GAS __attribute__((address_space(1)))
; __device__ __forceinline__ v4u pack8(const float* v) { v4u w; w.x = pk2(v[0], v[1]); w.y = pk2(v[2], v[3]); w.z = pk2(v[4], v[5]); w.w = pk2(v[6], v[7]); return w; }
;     __device__ __forceinline__ bool operator()(pg8::f32x4 (&acc)[2][2][4][2], const pg8::Unit& u, int wr, int wc, int fr, int fq) const {
;     ...
; #pragma unroll
;             for (int ai = 0; ai < 2; ++ai)
; #pragma unroll
;                 for (int m = 0; m < 4; ++m) {
;                     const size_t row = (size_t)(row0 + ai * 128 + m * 16);
;                     float ss = 0.f;
; #pragma unroll
;                     for (int bj = 0; bj < 2; ++bj)
; #pragma unroll
;                         for (int n = 0; n < 2; ++n) { const pg8::f32x4 a = acc[ai][bj][m][n]; ss += (a.x * a.x + a.y * a.y) + (a.z * a.z + a.w * a.w); }
;                     ss += __shfl_xor(ss, 16); ss += __shfl_xor(ss, 32);
;                     const float rinv = 1.f / sqrtf(ss * (1.f / 64.f) + EPS);
; #pragma unroll
;                     for (int bj = 0; bj < 2; ++bj) {
;                         float v[8];
; #pragma unroll
;                         for (int e = 0; e < 8; ++e) v[e] = acc[ai][bj][m][e >> 2][e & 3] * rinv * gv[bj][e];
;                         *(GAS v4u*)(dstb + row * DM + cb + bj * 32) = pack8(v);
;                         if (g == 3) { GAS f32x4* o = (GAS f32x4*)(kout + row * DM + cb + bj * 32); o[0] = (f32x4){v[0], v[1], v[2], v[3]}; o[1] = (f32x4){v[4], v[5], v[6], v[7]}; }
;                     }
.LBB0_329:
	s_nop 1
	v_pk_mul_f32 v[66:67], v[64:65], v[64:65]
	v_pk_mul_f32 v[68:69], v[62:63], v[62:63]
	s_nop 0
	v_pk_mov_b32 v[70:71], v[68:69], v[66:67] op_sel:[1,0]
	v_mov_b32_e32 v69, v67
	v_pk_add_f32 v[66:67], v[70:71], v[68:69]
	v_pk_mul_f32 v[68:69], v[60:61], v[60:61]
	v_pk_mul_f32 v[70:71], v[58:59], v[58:59]
	v_pk_add_f32 v[66:67], v[66:67], v[66:67] op_sel:[0,1] op_sel_hi:[1,0]
	v_pk_mov_b32 v[72:73], v[70:71], v[68:69] op_sel:[1,0]
	v_mov_b32_e32 v71, v69
	v_pk_add_f32 v[68:69], v[72:73], v[70:71]
	v_mul_f32_e32 v70, v50, v50
	v_mul_f32_e32 v71, v51, v51
	v_pk_add_f32 v[68:69], v[68:69], v[68:69] op_sel:[0,1] op_sel_hi:[1,0]
	v_mov_b32_e32 v67, v70
	v_mov_b32_e32 v69, v71
	v_pk_add_f32 v[66:67], v[66:67], v[68:69]
	v_mul_f32_e32 v68, v55, v55
	v_mul_f32_e32 v70, v57, v57
	v_mul_f32_e32 v72, v52, v52
	v_mul_f32_e32 v73, v53, v53
	v_pk_fma_f32 v[68:69], v[54:55], v[54:55], v[68:69] op_sel_hi:[1,1,0]
	v_pk_fma_f32 v[70:71], v[56:57], v[56:57], v[70:71] op_sel_hi:[1,1,0]
	v_mov_b32_e32 v69, v72
	v_mov_b32_e32 v71, v73
	v_pk_add_f32 v[68:69], v[68:69], v[70:71]
	s_nop 0
	v_pk_add_f32 v[66:67], v[66:67], v[68:69]
	s_nop 0
	v_add_f32_e32 v66, v66, v67
	ds_bpermute_b32 v67, v188, v66
	s_waitcnt lgkmcnt(0)
	v_add_f32_e32 v66, v66, v67
	ds_bpermute_b32 v67, v189, v66
	s_waitcnt lgkmcnt(0)
	v_add_f32_e32 v66, v66, v67
	v_fmamk_f32 v66, v66, 0x3c800000, v184
	v_mul_f32_e32 v67, 0x4f800000, v66
	v_cmp_gt_f32_e32 vcc, s61, v66
	s_nop 1
	v_cndmask_b32_e32 v66, v66, v67, vcc
	v_sqrt_f32_e32 v67, v66
	s_nop 0
	v_add_u32_e32 v68, -1, v67
	v_fma_f32 v69, -v68, v67, v66
	v_cmp_ge_f32_e64 s[6:7], 0, v69
	v_add_u32_e32 v69, 1, v67
	s_nop 0
	v_cndmask_b32_e64 v68, v67, v68, s[6:7]
	v_fma_f32 v67, -v69, v67, v66
	v_cmp_lt_f32_e64 s[6:7], 0, v67
	s_nop 1
	v_cndmask_b32_e64 v67, v68, v69, s[6:7]
	v_mul_f32_e32 v68, 0x37800000, v67
	v_cndmask_b32_e32 v67, v67, v68, vcc
	v_cmp_class_f32_e32 vcc, v66, v185
	s_nop 1
	v_cndmask_b32_e32 v68, v67, v66, vcc
	v_div_scale_f32 v69, s[6:7], v68, v68, 1.0
	v_rcp_f32_e32 v70, v69
	v_add_u32_e32 v66, 0x80, v164
	v_ashrrev_i32_e32 v67, 31, v66
	v_fma_f32 v71, -v69, v70, 1.0
	v_fmac_f32_e32 v70, v71, v70
	v_div_scale_f32 v71, vcc, 1.0, v68, 1.0
	v_mul_f32_e32 v72, v71, v70
	v_fma_f32 v73, -v69, v72, v71
	v_fmac_f32_e32 v72, v73, v70
	v_fma_f32 v69, -v69, v72, v71
	v_div_fmas_f32 v69, v69, v70, v72
	v_div_fixup_f32 v70, v69, v68, 1.0
	v_lshlrev_b64 v[68:69], 11, v[66:67]
	v_lshlrev_b64 v[66:67], 12, v[66:67]
	v_pk_mul_f32 v[62:63], v[62:63], v[70:71] op_sel_hi:[1,0]
	v_pk_mul_f32 v[64:65], v[64:65], v[70:71] op_sel_hi:[1,0]
	v_pk_mul_f32 v[58:59], v[58:59], v[70:71] op_sel_hi:[1,0]
	v_pk_mul_f32 v[60:61], v[60:61], v[70:71] op_sel_hi:[1,0]
	v_lshl_add_u64 v[68:69], v[166:167], 0, v[68:69]
	v_lshl_add_u64 v[66:67], v[132:133], 0, v[66:67]
	v_pk_mul_f32 v[62:63], v[168:169], v[62:63]
	v_pk_mul_f32 v[64:65], v[136:137], v[64:65]
	v_pk_mul_f32 v[58:59], v[134:135], v[58:59]
	v_pk_mul_f32 v[60:61], v[130:131], v[60:61]
	s_and_b64 vcc, exec, s[4:5]
	v_cvt_pk_bf16_f32 v72, v62, v63
	v_cvt_pk_bf16_f32 v73, v64, v65
	v_cvt_pk_bf16_f32 v74, v58, v59
	v_cvt_pk_bf16_f32 v75, v60, v61
	ds_write_b128 v232, v[72:75]
	s_cbranch_vccnz .LBB0_331
	ds_write_b128 v235, v[62:65]
	ds_write_b128 v235, v[58:61] offset:16
	ds_read_b128 v[238:241], v236
	ds_read_b128 v[242:245], v236 offset:1152
	v_lshl_add_u64 v[246:247], v[66:67], 0, v[252:253]
	v_lshl_add_u64 v[248:249], v[246:247], 0, s[100:101]
	s_waitcnt lgkmcnt(0)
	global_store_dwordx4 v[246:247], v[238:241], off
	global_store_dwordx4 v[248:249], v[242:245], off
.LBB0_331:
	v_mov_b32_e32 v71, v70
	v_pk_mul_f32 v[54:55], v[54:55], v[70:71]
	v_pk_mul_f32 v[56:57], v[56:57], v[70:71]
	v_pk_mul_f32 v[50:51], v[50:51], v[70:71]
	v_pk_mul_f32 v[52:53], v[52:53], v[70:71]
	v_pk_mul_f32 v[54:55], v[128:129], v[54:55]
	v_pk_mul_f32 v[56:57], v[126:127], v[56:57]
	v_pk_mul_f32 v[50:51], v[124:125], v[50:51]
	v_pk_mul_f32 v[52:53], v[122:123], v[52:53]
	s_and_b64 vcc, exec, s[4:5]
	v_cvt_pk_bf16_f32 v58, v54, v55
	v_cvt_pk_bf16_f32 v59, v56, v57
	v_cvt_pk_bf16_f32 v60, v50, v51
	v_cvt_pk_bf16_f32 v61, v52, v53
	ds_write_b128 v233, v[58:61]
	ds_read_b128 v[238:241], v234
	ds_read_b128 v[242:245], v234 offset:8192
	v_lshl_add_u64 v[246:247], v[68:69], 0, v[250:251]
	v_lshl_add_u64 v[248:249], v[246:247], 0, s[98:99]
	s_waitcnt lgkmcnt(0)
	global_store_dwordx4 v[246:247], v[238:241], off
	global_store_dwordx4 v[248:249], v[242:245], off
	s_cbranch_vccnz .LBB0_333
	ds_write_b128 v235, v[54:57]
	ds_write_b128 v235, v[50:53] offset:16
	ds_read_b128 v[238:241], v236
	ds_read_b128 v[242:245], v236 offset:1152
	v_lshl_add_u64 v[246:247], v[66:67], 0, v[252:253]
	v_lshl_add_u64 v[248:249], v[246:247], 0, s[100:101]
	s_waitcnt lgkmcnt(0)
	global_store_dwordx4 v[246:247], v[238:241], off offset:128
	global_store_dwordx4 v[248:249], v[242:245], off offset:128
; #define GAS __attribute__((address_space(1)))
; __device__ __forceinline__ v4u pack8(const float* v) { v4u w; w.x = pk2(v[0], v[1]); w.y = pk2(v[2], v[3]); w.z = pk2(v[4], v[5]); w.w = pk2(v[6], v[7]); return w; }
;     __device__ __forceinline__ bool operator()(pg8::f32x4 (&acc)[2][2][4][2], const pg8::Unit& u, int wr, int wc, int fr, int fq) const {
;     ...
; #pragma unroll
;             for (int ai = 0; ai < 2; ++ai)
; #pragma unroll
;                 for (int m = 0; m < 4; ++m) {
;                     const size_t row = (size_t)(row0 + ai * 128 + m * 16);
;                     float ss = 0.f;
; #pragma unroll
;                     for (int bj = 0; bj < 2; ++bj)
; #pragma unroll
;                         for (int n = 0; n < 2; ++n) { const pg8::f32x4 a = acc[ai][bj][m][n]; ss += (a.x * a.x + a.y * a.y) + (a.z * a.z + a.w * a.w); }
;                     ss += __shfl_xor(ss, 16); ss += __shfl_xor(ss, 32);
;                     const float rinv = 1.f / sqrtf(ss * (1.f / 64.f) + EPS);
; #pragma unroll
;                     for (int bj = 0; bj < 2; ++bj) {
;                         float v[8];
; #pragma unroll
;                         for (int e = 0; e < 8; ++e) v[e] = acc[ai][bj][m][e >> 2][e & 3] * rinv * gv[bj][e];
;                         *(GAS v4u*)(dstb + row * DM + cb + bj * 32) = pack8(v);
;                         if (g == 3) { GAS f32x4* o = (GAS f32x4*)(kout + row * DM + cb + bj * 32); o[0] = (f32x4){v[0], v[1], v[2], v[3]}; o[1] = (f32x4){v[4], v[5], v[6], v[7]}; }
;                     }
.LBB0_333:
	s_nop 1
	v_pk_mul_f32 v[50:51], v[48:49], v[48:49]
	v_pk_mul_f32 v[52:53], v[46:47], v[46:47]
	s_nop 0
	v_pk_mov_b32 v[54:55], v[52:53], v[50:51] op_sel:[1,0]
	v_mov_b32_e32 v53, v51
	v_pk_add_f32 v[50:51], v[54:55], v[52:53]
	v_pk_mul_f32 v[52:53], v[44:45], v[44:45]
	v_pk_mul_f32 v[54:55], v[42:43], v[42:43]
	v_pk_add_f32 v[50:51], v[50:51], v[50:51] op_sel:[0,1] op_sel_hi:[1,0]
	v_pk_mov_b32 v[56:57], v[54:55], v[52:53] op_sel:[1,0]
	v_mov_b32_e32 v55, v53
	v_pk_add_f32 v[52:53], v[56:57], v[54:55]
	v_mul_f32_e32 v54, v34, v34
	v_mul_f32_e32 v55, v35, v35
	v_pk_add_f32 v[52:53], v[52:53], v[52:53] op_sel:[0,1] op_sel_hi:[1,0]
	v_mov_b32_e32 v51, v54
	v_mov_b32_e32 v53, v55
	v_pk_add_f32 v[50:51], v[50:51], v[52:53]
	v_mul_f32_e32 v52, v39, v39
	v_mul_f32_e32 v54, v41, v41
	v_mul_f32_e32 v56, v36, v36
	v_mul_f32_e32 v57, v37, v37
	v_pk_fma_f32 v[52:53], v[38:39], v[38:39], v[52:53] op_sel_hi:[1,1,0]
	v_pk_fma_f32 v[54:55], v[40:41], v[40:41], v[54:55] op_sel_hi:[1,1,0]
	v_mov_b32_e32 v53, v56
	v_mov_b32_e32 v55, v57
	v_pk_add_f32 v[52:53], v[52:53], v[54:55]
	s_nop 0
	v_pk_add_f32 v[50:51], v[50:51], v[52:53]
	s_nop 0
	v_add_f32_e32 v50, v50, v51
	ds_bpermute_b32 v51, v188, v50
	s_waitcnt lgkmcnt(0)
	v_add_f32_e32 v50, v50, v51
	ds_bpermute_b32 v51, v189, v50
	s_waitcnt lgkmcnt(0)
	v_add_f32_e32 v50, v50, v51
	v_fmamk_f32 v50, v50, 0x3c800000, v184
	v_mul_f32_e32 v51, 0x4f800000, v50
	v_cmp_gt_f32_e32 vcc, s61, v50
	s_nop 1
	v_cndmask_b32_e32 v50, v50, v51, vcc
	v_sqrt_f32_e32 v51, v50
	s_nop 0
	v_add_u32_e32 v52, -1, v51
	v_fma_f32 v53, -v52, v51, v50
	v_cmp_ge_f32_e64 s[6:7], 0, v53
	v_add_u32_e32 v53, 1, v51
	s_nop 0
	v_cndmask_b32_e64 v52, v51, v52, s[6:7]
	v_fma_f32 v51, -v53, v51, v50
	v_cmp_lt_f32_e64 s[6:7], 0, v51
	s_nop 1
	v_cndmask_b32_e64 v51, v52, v53, s[6:7]
	v_mul_f32_e32 v52, 0x37800000, v51
	v_cndmask_b32_e32 v51, v51, v52, vcc
	v_cmp_class_f32_e32 vcc, v50, v185
	s_nop 1
	v_cndmask_b32_e32 v52, v51, v50, vcc
	v_div_scale_f32 v53, s[6:7], v52, v52, 1.0
	v_rcp_f32_e32 v54, v53
	v_add_u32_e32 v50, 0x90, v164
	v_ashrrev_i32_e32 v51, 31, v50
	v_fma_f32 v55, -v53, v54, 1.0
	v_fmac_f32_e32 v54, v55, v54
	v_div_scale_f32 v55, vcc, 1.0, v52, 1.0
	v_mul_f32_e32 v56, v55, v54
	v_fma_f32 v57, -v53, v56, v55
	v_fmac_f32_e32 v56, v57, v54
	v_fma_f32 v53, -v53, v56, v55
	v_div_fmas_f32 v53, v53, v54, v56
	v_div_fixup_f32 v54, v53, v52, 1.0
	v_lshlrev_b64 v[52:53], 11, v[50:51]
	v_lshlrev_b64 v[50:51], 12, v[50:51]
	v_pk_mul_f32 v[46:47], v[46:47], v[54:55] op_sel_hi:[1,0]
	v_pk_mul_f32 v[48:49], v[48:49], v[54:55] op_sel_hi:[1,0]
	v_pk_mul_f32 v[42:43], v[42:43], v[54:55] op_sel_hi:[1,0]
	v_pk_mul_f32 v[44:45], v[44:45], v[54:55] op_sel_hi:[1,0]
	v_lshl_add_u64 v[52:53], v[166:167], 0, v[52:53]
	v_lshl_add_u64 v[50:51], v[132:133], 0, v[50:51]
	v_pk_mul_f32 v[46:47], v[168:169], v[46:47]
	v_pk_mul_f32 v[48:49], v[136:137], v[48:49]
	v_pk_mul_f32 v[42:43], v[134:135], v[42:43]
	v_pk_mul_f32 v[44:45], v[130:131], v[44:45]
	s_and_b64 vcc, exec, s[4:5]
	v_cvt_pk_bf16_f32 v56, v46, v47
	v_cvt_pk_bf16_f32 v57, v48, v49
	v_cvt_pk_bf16_f32 v58, v42, v43
	v_cvt_pk_bf16_f32 v59, v44, v45
	ds_write_b128 v232, v[56:59]
	s_cbranch_vccnz .LBB0_335
	ds_write_b128 v235, v[46:49]
	ds_write_b128 v235, v[42:45] offset:16
	ds_read_b128 v[238:241], v236
	ds_read_b128 v[242:245], v236 offset:1152
	v_lshl_add_u64 v[246:247], v[50:51], 0, v[252:253]
	v_lshl_add_u64 v[248:249], v[246:247], 0, s[100:101]
	s_waitcnt lgkmcnt(0)
	global_store_dwordx4 v[246:247], v[238:241], off
	global_store_dwordx4 v[248:249], v[242:245], off
.LBB0_335:
	v_mov_b32_e32 v55, v54
	v_pk_mul_f32 v[38:39], v[38:39], v[54:55]
	v_pk_mul_f32 v[40:41], v[40:41], v[54:55]
	v_pk_mul_f32 v[34:35], v[34:35], v[54:55]
	v_pk_mul_f32 v[36:37], v[36:37], v[54:55]
	v_pk_mul_f32 v[38:39], v[128:129], v[38:39]
	v_pk_mul_f32 v[40:41], v[126:127], v[40:41]
	v_pk_mul_f32 v[34:35], v[124:125], v[34:35]
	v_pk_mul_f32 v[36:37], v[122:123], v[36:37]
	s_and_b64 vcc, exec, s[4:5]
	v_cvt_pk_bf16_f32 v42, v38, v39
	v_cvt_pk_bf16_f32 v43, v40, v41
	v_cvt_pk_bf16_f32 v44, v34, v35
	v_cvt_pk_bf16_f32 v45, v36, v37
	ds_write_b128 v233, v[42:45]
	ds_read_b128 v[238:241], v234
	ds_read_b128 v[242:245], v234 offset:8192
	v_lshl_add_u64 v[246:247], v[52:53], 0, v[250:251]
	v_lshl_add_u64 v[248:249], v[246:247], 0, s[98:99]
	s_waitcnt lgkmcnt(0)
	global_store_dwordx4 v[246:247], v[238:241], off
	global_store_dwordx4 v[248:249], v[242:245], off
	s_cbranch_vccnz .LBB0_337
	ds_write_b128 v235, v[38:41]
	ds_write_b128 v235, v[34:37] offset:16
	ds_read_b128 v[238:241], v236
	ds_read_b128 v[242:245], v236 offset:1152
	v_lshl_add_u64 v[246:247], v[50:51], 0, v[252:253]
	v_lshl_add_u64 v[248:249], v[246:247], 0, s[100:101]
	s_waitcnt lgkmcnt(0)
	global_store_dwordx4 v[246:247], v[238:241], off offset:128
	global_store_dwordx4 v[248:249], v[242:245], off offset:128
; #define GAS __attribute__((address_space(1)))
; __device__ __forceinline__ v4u pack8(const float* v) { v4u w; w.x = pk2(v[0], v[1]); w.y = pk2(v[2], v[3]); w.z = pk2(v[4], v[5]); w.w = pk2(v[6], v[7]); return w; }
;     __device__ __forceinline__ bool operator()(pg8::f32x4 (&acc)[2][2][4][2], const pg8::Unit& u, int wr, int wc, int fr, int fq) const {
;     ...
; #pragma unroll
;             for (int ai = 0; ai < 2; ++ai)
; #pragma unroll
;                 for (int m = 0; m < 4; ++m) {
;                     const size_t row = (size_t)(row0 + ai * 128 + m * 16);
;                     float ss = 0.f;
; #pragma unroll
;                     for (int bj = 0; bj < 2; ++bj)
; #pragma unroll
;                         for (int n = 0; n < 2; ++n) { const pg8::f32x4 a = acc[ai][bj][m][n]; ss += (a.x * a.x + a.y * a.y) + (a.z * a.z + a.w * a.w); }
;                     ss += __shfl_xor(ss, 16); ss += __shfl_xor(ss, 32);
;                     const float rinv = 1.f / sqrtf(ss * (1.f / 64.f) + EPS);
; #pragma unroll
;                     for (int bj = 0; bj < 2; ++bj) {
;                         float v[8];
; #pragma unroll
;                         for (int e = 0; e < 8; ++e) v[e] = acc[ai][bj][m][e >> 2][e & 3] * rinv * gv[bj][e];
;                         *(GAS v4u*)(dstb + row * DM + cb + bj * 32) = pack8(v);
;                         if (g == 3) { GAS f32x4* o = (GAS f32x4*)(kout + row * DM + cb + bj * 32); o[0] = (f32x4){v[0], v[1], v[2], v[3]}; o[1] = (f32x4){v[4], v[5], v[6], v[7]}; }
;                     }
.LBB0_337:
	s_nop 1
	v_pk_mul_f32 v[34:35], v[32:33], v[32:33]
	v_pk_mul_f32 v[36:37], v[30:31], v[30:31]
	s_nop 0
	v_pk_mov_b32 v[38:39], v[36:37], v[34:35] op_sel:[1,0]
	v_mov_b32_e32 v37, v35
	v_pk_add_f32 v[34:35], v[38:39], v[36:37]
	v_pk_mul_f32 v[36:37], v[28:29], v[28:29]
	v_pk_mul_f32 v[38:39], v[26:27], v[26:27]
	v_pk_add_f32 v[34:35], v[34:35], v[34:35] op_sel:[0,1] op_sel_hi:[1,0]
	v_pk_mov_b32 v[40:41], v[38:39], v[36:37] op_sel:[1,0]
	v_mov_b32_e32 v39, v37
	v_pk_add_f32 v[36:37], v[40:41], v[38:39]
	v_mul_f32_e32 v38, v18, v18
	v_mul_f32_e32 v39, v19, v19
	v_pk_add_f32 v[36:37], v[36:37], v[36:37] op_sel:[0,1] op_sel_hi:[1,0]
	v_mov_b32_e32 v35, v38
	v_mov_b32_e32 v37, v39
	v_pk_add_f32 v[34:35], v[34:35], v[36:37]
	v_mul_f32_e32 v36, v23, v23
	v_mul_f32_e32 v38, v25, v25
	v_mul_f32_e32 v40, v20, v20
	v_mul_f32_e32 v41, v21, v21
	v_pk_fma_f32 v[36:37], v[22:23], v[22:23], v[36:37] op_sel_hi:[1,1,0]
	v_pk_fma_f32 v[38:39], v[24:25], v[24:25], v[38:39] op_sel_hi:[1,1,0]
	v_mov_b32_e32 v37, v40
	v_mov_b32_e32 v39, v41
	v_pk_add_f32 v[36:37], v[36:37], v[38:39]
	s_nop 0
	v_pk_add_f32 v[34:35], v[34:35], v[36:37]
	s_nop 0
	v_add_f32_e32 v34, v34, v35
	ds_bpermute_b32 v35, v188, v34
	s_waitcnt lgkmcnt(0)
	v_add_f32_e32 v34, v34, v35
	ds_bpermute_b32 v35, v189, v34
	s_waitcnt lgkmcnt(0)
	v_add_f32_e32 v34, v34, v35
	v_fmamk_f32 v34, v34, 0x3c800000, v184
	v_mul_f32_e32 v35, 0x4f800000, v34
	v_cmp_gt_f32_e32 vcc, s61, v34
	s_nop 1
	v_cndmask_b32_e32 v34, v34, v35, vcc
	v_sqrt_f32_e32 v35, v34
	s_nop 0
	v_add_u32_e32 v36, -1, v35
	v_fma_f32 v37, -v36, v35, v34
	v_cmp_ge_f32_e64 s[6:7], 0, v37
	v_add_u32_e32 v37, 1, v35
	s_nop 0
	v_cndmask_b32_e64 v36, v35, v36, s[6:7]
	v_fma_f32 v35, -v37, v35, v34
	v_cmp_lt_f32_e64 s[6:7], 0, v35
	s_nop 1
	v_cndmask_b32_e64 v35, v36, v37, s[6:7]
	v_mul_f32_e32 v36, 0x37800000, v35
	v_cndmask_b32_e32 v35, v35, v36, vcc
	v_cmp_class_f32_e32 vcc, v34, v185
	s_nop 1
	v_cndmask_b32_e32 v36, v35, v34, vcc
	v_div_scale_f32 v37, s[6:7], v36, v36, 1.0
	v_rcp_f32_e32 v38, v37
	v_add_u32_e32 v34, 0xa0, v164
	v_ashrrev_i32_e32 v35, 31, v34
	v_fma_f32 v39, -v37, v38, 1.0
	v_fmac_f32_e32 v38, v39, v38
	v_div_scale_f32 v39, vcc, 1.0, v36, 1.0
	v_mul_f32_e32 v40, v39, v38
	v_fma_f32 v41, -v37, v40, v39
	v_fmac_f32_e32 v40, v41, v38
	v_fma_f32 v37, -v37, v40, v39
	v_div_fmas_f32 v37, v37, v38, v40
	v_div_fixup_f32 v38, v37, v36, 1.0
	v_lshlrev_b64 v[36:37], 11, v[34:35]
	v_lshlrev_b64 v[34:35], 12, v[34:35]
	v_pk_mul_f32 v[30:31], v[30:31], v[38:39] op_sel_hi:[1,0]
	v_pk_mul_f32 v[32:33], v[32:33], v[38:39] op_sel_hi:[1,0]
	v_pk_mul_f32 v[26:27], v[26:27], v[38:39] op_sel_hi:[1,0]
	v_pk_mul_f32 v[28:29], v[28:29], v[38:39] op_sel_hi:[1,0]
	v_lshl_add_u64 v[36:37], v[166:167], 0, v[36:37]
	v_lshl_add_u64 v[34:35], v[132:133], 0, v[34:35]
	v_pk_mul_f32 v[30:31], v[168:169], v[30:31]
	v_pk_mul_f32 v[32:33], v[136:137], v[32:33]
	v_pk_mul_f32 v[26:27], v[134:135], v[26:27]
	v_pk_mul_f32 v[28:29], v[130:131], v[28:29]
	s_and_b64 vcc, exec, s[4:5]
	v_cvt_pk_bf16_f32 v40, v30, v31
	v_cvt_pk_bf16_f32 v41, v32, v33
	v_cvt_pk_bf16_f32 v42, v26, v27
	v_cvt_pk_bf16_f32 v43, v28, v29
	ds_write_b128 v232, v[40:43]
	s_cbranch_vccnz .LBB0_339
	ds_write_b128 v235, v[30:33]
	ds_write_b128 v235, v[26:29] offset:16
	ds_read_b128 v[238:241], v236
	ds_read_b128 v[242:245], v236 offset:1152
	v_lshl_add_u64 v[246:247], v[34:35], 0, v[252:253]
	v_lshl_add_u64 v[248:249], v[246:247], 0, s[100:101]
	s_waitcnt lgkmcnt(0)
	global_store_dwordx4 v[246:247], v[238:241], off
	global_store_dwordx4 v[248:249], v[242:245], off
.LBB0_339:
	v_mov_b32_e32 v39, v38
	v_pk_mul_f32 v[22:23], v[22:23], v[38:39]
	v_pk_mul_f32 v[24:25], v[24:25], v[38:39]
	v_pk_mul_f32 v[18:19], v[18:19], v[38:39]
	v_pk_mul_f32 v[20:21], v[20:21], v[38:39]
	v_pk_mul_f32 v[22:23], v[128:129], v[22:23]
	v_pk_mul_f32 v[24:25], v[126:127], v[24:25]
	v_pk_mul_f32 v[18:19], v[124:125], v[18:19]
	v_pk_mul_f32 v[20:21], v[122:123], v[20:21]
	s_and_b64 vcc, exec, s[4:5]
	v_cvt_pk_bf16_f32 v26, v22, v23
	v_cvt_pk_bf16_f32 v27, v24, v25
	v_cvt_pk_bf16_f32 v28, v18, v19
	v_cvt_pk_bf16_f32 v29, v20, v21
	ds_write_b128 v233, v[26:29]
	ds_read_b128 v[238:241], v234
	ds_read_b128 v[242:245], v234 offset:8192
	v_lshl_add_u64 v[246:247], v[36:37], 0, v[250:251]
	v_lshl_add_u64 v[248:249], v[246:247], 0, s[98:99]
	s_waitcnt lgkmcnt(0)
	global_store_dwordx4 v[246:247], v[238:241], off
	global_store_dwordx4 v[248:249], v[242:245], off
	s_cbranch_vccnz .LBB0_341
	ds_write_b128 v235, v[22:25]
	ds_write_b128 v235, v[18:21] offset:16
	ds_read_b128 v[238:241], v236
	ds_read_b128 v[242:245], v236 offset:1152
	v_lshl_add_u64 v[246:247], v[34:35], 0, v[252:253]
	v_lshl_add_u64 v[248:249], v[246:247], 0, s[100:101]
	s_waitcnt lgkmcnt(0)
	global_store_dwordx4 v[246:247], v[238:241], off offset:128
	global_store_dwordx4 v[248:249], v[242:245], off offset:128
; #define GAS __attribute__((address_space(1)))
; __device__ __forceinline__ v4u pack8(const float* v) { v4u w; w.x = pk2(v[0], v[1]); w.y = pk2(v[2], v[3]); w.z = pk2(v[4], v[5]); w.w = pk2(v[6], v[7]); return w; }
;     __device__ __forceinline__ bool operator()(pg8::f32x4 (&acc)[2][2][4][2], const pg8::Unit& u, int wr, int wc, int fr, int fq) const {
;     ...
; #pragma unroll
;             for (int ai = 0; ai < 2; ++ai)
; #pragma unroll
;                 for (int m = 0; m < 4; ++m) {
;                     const size_t row = (size_t)(row0 + ai * 128 + m * 16);
;                     float ss = 0.f;
; #pragma unroll
;                     for (int bj = 0; bj < 2; ++bj)
; #pragma unroll
;                         for (int n = 0; n < 2; ++n) { const pg8::f32x4 a = acc[ai][bj][m][n]; ss += (a.x * a.x + a.y * a.y) + (a.z * a.z + a.w * a.w); }
;                     ss += __shfl_xor(ss, 16); ss += __shfl_xor(ss, 32);
;                     const float rinv = 1.f / sqrtf(ss * (1.f / 64.f) + EPS);
; #pragma unroll
;                     for (int bj = 0; bj < 2; ++bj) {
;                         float v[8];
; #pragma unroll
;                         for (int e = 0; e < 8; ++e) v[e] = acc[ai][bj][m][e >> 2][e & 3] * rinv * gv[bj][e];
;                         *(GAS v4u*)(dstb + row * DM + cb + bj * 32) = pack8(v);
;                         if (g == 3) { GAS f32x4* o = (GAS f32x4*)(kout + row * DM + cb + bj * 32); o[0] = (f32x4){v[0], v[1], v[2], v[3]}; o[1] = (f32x4){v[4], v[5], v[6], v[7]}; }
;                     }
.LBB0_341:
	s_nop 1
	v_pk_mul_f32 v[18:19], v[16:17], v[16:17]
	v_pk_mul_f32 v[20:21], v[14:15], v[14:15]
	s_nop 0
	v_pk_mov_b32 v[22:23], v[20:21], v[18:19] op_sel:[1,0]
	v_mov_b32_e32 v21, v19
	v_pk_add_f32 v[18:19], v[22:23], v[20:21]
	v_pk_mul_f32 v[20:21], v[12:13], v[12:13]
	v_pk_mul_f32 v[22:23], v[10:11], v[10:11]
	v_pk_add_f32 v[18:19], v[18:19], v[18:19] op_sel:[0,1] op_sel_hi:[1,0]
	v_pk_mov_b32 v[24:25], v[22:23], v[20:21] op_sel:[1,0]
	v_mov_b32_e32 v23, v21
	v_pk_add_f32 v[20:21], v[24:25], v[22:23]
	v_mul_f32_e32 v22, v2, v2
	v_mul_f32_e32 v23, v3, v3
	v_pk_add_f32 v[20:21], v[20:21], v[20:21] op_sel:[0,1] op_sel_hi:[1,0]
	v_mov_b32_e32 v19, v22
	v_mov_b32_e32 v21, v23
	v_pk_add_f32 v[18:19], v[18:19], v[20:21]
	v_mul_f32_e32 v20, v7, v7
	v_mul_f32_e32 v22, v9, v9
	v_mul_f32_e32 v24, v4, v4
	v_mul_f32_e32 v25, v5, v5
	v_pk_fma_f32 v[20:21], v[6:7], v[6:7], v[20:21] op_sel_hi:[1,1,0]
	v_pk_fma_f32 v[22:23], v[8:9], v[8:9], v[22:23] op_sel_hi:[1,1,0]
	v_mov_b32_e32 v21, v24
	v_mov_b32_e32 v23, v25
	v_pk_add_f32 v[20:21], v[20:21], v[22:23]
	s_nop 0
	v_pk_add_f32 v[18:19], v[18:19], v[20:21]
	s_nop 0
	v_add_f32_e32 v18, v18, v19
	ds_bpermute_b32 v19, v188, v18
	s_waitcnt lgkmcnt(0)
	v_add_f32_e32 v18, v18, v19
	ds_bpermute_b32 v19, v189, v18
	s_waitcnt lgkmcnt(0)
	v_add_f32_e32 v18, v18, v19
	v_fmamk_f32 v18, v18, 0x3c800000, v184
	v_mul_f32_e32 v19, 0x4f800000, v18
	v_cmp_gt_f32_e32 vcc, s61, v18
	s_nop 1
	v_cndmask_b32_e32 v18, v18, v19, vcc
	v_sqrt_f32_e32 v19, v18
	s_nop 0
	v_add_u32_e32 v20, -1, v19
	v_fma_f32 v21, -v20, v19, v18
	v_cmp_ge_f32_e64 s[6:7], 0, v21
	v_add_u32_e32 v21, 1, v19
	s_nop 0
	v_cndmask_b32_e64 v20, v19, v20, s[6:7]
	v_fma_f32 v19, -v21, v19, v18
	v_cmp_lt_f32_e64 s[6:7], 0, v19
	s_nop 1
	v_cndmask_b32_e64 v19, v20, v21, s[6:7]
	v_mul_f32_e32 v20, 0x37800000, v19
	v_cndmask_b32_e32 v19, v19, v20, vcc
	v_cmp_class_f32_e32 vcc, v18, v185
	s_nop 1
	v_cndmask_b32_e32 v20, v19, v18, vcc
	v_div_scale_f32 v21, s[6:7], v20, v20, 1.0
	v_rcp_f32_e32 v22, v21
	v_add_u32_e32 v18, 0xb0, v164
	v_ashrrev_i32_e32 v19, 31, v18
	v_fma_f32 v23, -v21, v22, 1.0
	v_fmac_f32_e32 v22, v23, v22
	v_div_scale_f32 v23, vcc, 1.0, v20, 1.0
	v_mul_f32_e32 v24, v23, v22
	v_fma_f32 v25, -v21, v24, v23
	v_fmac_f32_e32 v24, v25, v22
	v_fma_f32 v21, -v21, v24, v23
	v_div_fmas_f32 v21, v21, v22, v24
	v_div_fixup_f32 v22, v21, v20, 1.0
	v_lshlrev_b64 v[20:21], 11, v[18:19]
	v_lshlrev_b64 v[18:19], 12, v[18:19]
	v_pk_mul_f32 v[14:15], v[14:15], v[22:23] op_sel_hi:[1,0]
	v_pk_mul_f32 v[16:17], v[16:17], v[22:23] op_sel_hi:[1,0]
	v_pk_mul_f32 v[10:11], v[10:11], v[22:23] op_sel_hi:[1,0]
	v_pk_mul_f32 v[12:13], v[12:13], v[22:23] op_sel_hi:[1,0]
	v_lshl_add_u64 v[20:21], v[166:167], 0, v[20:21]
	v_lshl_add_u64 v[18:19], v[132:133], 0, v[18:19]
	v_pk_mul_f32 v[14:15], v[168:169], v[14:15]
	v_pk_mul_f32 v[16:17], v[136:137], v[16:17]
	v_pk_mul_f32 v[10:11], v[134:135], v[10:11]
	v_pk_mul_f32 v[12:13], v[130:131], v[12:13]
	s_and_b64 vcc, exec, s[4:5]
	v_cvt_pk_bf16_f32 v24, v14, v15
	v_cvt_pk_bf16_f32 v25, v16, v17
	v_cvt_pk_bf16_f32 v26, v10, v11
	v_cvt_pk_bf16_f32 v27, v12, v13
	ds_write_b128 v232, v[24:27]
	s_cbranch_vccnz .LBB0_343
	ds_write_b128 v235, v[14:17]
	ds_write_b128 v235, v[10:13] offset:16
	ds_read_b128 v[238:241], v236
	ds_read_b128 v[242:245], v236 offset:1152
	v_lshl_add_u64 v[246:247], v[18:19], 0, v[252:253]
	v_lshl_add_u64 v[248:249], v[246:247], 0, s[100:101]
	s_waitcnt lgkmcnt(0)
	global_store_dwordx4 v[246:247], v[238:241], off
	global_store_dwordx4 v[248:249], v[242:245], off
.LBB0_343:
	v_mov_b32_e32 v23, v22
	v_pk_mul_f32 v[6:7], v[6:7], v[22:23]
	v_pk_mul_f32 v[8:9], v[8:9], v[22:23]
	v_pk_mul_f32 v[2:3], v[2:3], v[22:23]
	v_pk_mul_f32 v[4:5], v[4:5], v[22:23]
	v_pk_mul_f32 v[6:7], v[128:129], v[6:7]
	v_pk_mul_f32 v[8:9], v[126:127], v[8:9]
	v_pk_mul_f32 v[2:3], v[124:125], v[2:3]
	v_pk_mul_f32 v[4:5], v[122:123], v[4:5]
	s_and_b64 vcc, exec, s[4:5]
	v_cvt_pk_bf16_f32 v10, v6, v7
	v_cvt_pk_bf16_f32 v11, v8, v9
	v_cvt_pk_bf16_f32 v12, v2, v3
	v_cvt_pk_bf16_f32 v13, v4, v5
	ds_write_b128 v233, v[10:13]
	ds_read_b128 v[238:241], v234
	ds_read_b128 v[242:245], v234 offset:8192
	v_lshl_add_u64 v[246:247], v[20:21], 0, v[250:251]
	v_lshl_add_u64 v[248:249], v[246:247], 0, s[98:99]
	s_waitcnt lgkmcnt(0)
	global_store_dwordx4 v[246:247], v[238:241], off
	global_store_dwordx4 v[248:249], v[242:245], off
	s_cbranch_vccnz .LBB0_345
	ds_write_b128 v235, v[6:9]
	ds_write_b128 v235, v[2:5] offset:16
	ds_read_b128 v[238:241], v236
	ds_read_b128 v[242:245], v236 offset:1152
	v_lshl_add_u64 v[246:247], v[18:19], 0, v[252:253]
	v_lshl_add_u64 v[248:249], v[246:247], 0, s[100:101]
	s_waitcnt lgkmcnt(0)
	global_store_dwordx4 v[246:247], v[238:241], off offset:128
	global_store_dwordx4 v[248:249], v[242:245], off offset:128

; __global__ void __launch_bounds__(NWAVES * 64, 2) skel_fwd(Args args) {
;     extern __shared__ __attribute__((aligned(16))) unsigned char lds[];
	.amdhsa_kernel _Z8skel_fwd4Args
		.amdhsa_group_segment_fixed_size 8192
		.amdhsa_private_segment_fixed_size 0
		.amdhsa_kernarg_size 496
		.amdhsa_user_sgpr_count 2
		.amdhsa_user_sgpr_dispatch_ptr 0
		.amdhsa_user_sgpr_queue_ptr 0
		.amdhsa_user_sgpr_kernarg_segment_ptr 1
		.amdhsa_user_sgpr_dispatch_id 0
		.amdhsa_user_sgpr_kernarg_preload_length 0
		.amdhsa_user_sgpr_kernarg_preload_offset 0
		.amdhsa_user_sgpr_private_segment_size 0
		.amdhsa_uses_dynamic_stack 0
		.amdhsa_enable_private_segment 0
		.amdhsa_system_sgpr_workgroup_id_x 1
		.amdhsa_system_sgpr_workgroup_id_y 0
		.amdhsa_system_sgpr_workgroup_id_z 0
		.amdhsa_system_sgpr_workgroup_info 0
		.amdhsa_system_vgpr_workitem_id 0
		.amdhsa_next_free_vgpr 256
		.amdhsa_next_free_sgpr 102
		.amdhsa_accum_offset 256
		.amdhsa_reserve_vcc 1
		.amdhsa_float_round_mode_32 0
		.amdhsa_float_round_mode_16_64 0
		.amdhsa_float_denorm_mode_32 3
		.amdhsa_float_denorm_mode_16_64 3
		.amdhsa_dx10_clamp 1
		.amdhsa_ieee_mode 1
		.amdhsa_fp16_overflow 0
		.amdhsa_tg_split 0
		.amdhsa_exception_fp_ieee_invalid_op 0
		.amdhsa_exception_fp_denorm_src 0
		.amdhsa_exception_fp_ieee_div_zero 0
		.amdhsa_exception_fp_ieee_overflow 0
		.amdhsa_exception_fp_ieee_underflow 0
		.amdhsa_exception_fp_ieee_inexact 0
		.amdhsa_exception_int_div_zero 0
	.end_amdhsa_kernel

; __global__ void __launch_bounds__(NWAVES * 64, 2) skel_fwd(Args args) {
;     extern __shared__ __attribute__((aligned(16))) unsigned char lds[];
amdhsa.kernels:
  - .agpr_count:     0
    .args:
      - .offset:         0
        .size:           240
        .value_kind:     by_value
      - .offset:         240
        .size:           4
        .value_kind:     hidden_block_count_x
      - .offset:         244
        .size:           4
        .value_kind:     hidden_block_count_y
      - .offset:         248
        .size:           4
        .value_kind:     hidden_block_count_z
      - .offset:         252
        .size:           2
        .value_kind:     hidden_group_size_x
      - .offset:         254
        .size:           2
        .value_kind:     hidden_group_size_y
      - .offset:         256
        .size:           2
        .value_kind:     hidden_group_size_z
      - .offset:         258
        .size:           2
        .value_kind:     hidden_remainder_x
      - .offset:         260
        .size:           2
        .value_kind:     hidden_remainder_y
      - .offset:         262
        .size:           2
        .value_kind:     hidden_remainder_z
      - .offset:         280
        .size:           8
        .value_kind:     hidden_global_offset_x
      - .offset:         288
        .size:           8
        .value_kind:     hidden_global_offset_y
      - .offset:         296
        .size:           8
        .value_kind:     hidden_global_offset_z
      - .offset:         304
        .size:           2
        .value_kind:     hidden_grid_dims
      - .offset:         360
        .size:           4
        .value_kind:     hidden_dynamic_lds_size
    .group_segment_fixed_size: 8192
    .kernarg_segment_align: 8
    .kernarg_segment_size: 496
    .language:       OpenCL C
    .language_version:
      - 2
      - 0
    .max_flat_workgroup_size: 512
    .name:           _Z8skel_fwd4Args
    .private_segment_fixed_size: 0
    .sgpr_count:     108
    .sgpr_spill_count: 37
    .symbol:         _Z8skel_fwd4Args.kd
    .uniform_work_group_size: 1
    .uses_dynamic_stack: false
    .vgpr_count:     256
    .vgpr_spill_count: 0
    .wavefront_size: 64
